# P5 pool/conv loops hand-rewritten: block-prefetched loads, scalar control flow, identical f32 arithmetic
# speedup vs baseline: 1.0024x; 1.0024x over previous
.LBB0_801:
	s_add_u32 s16, s34, 0x2b500000
	s_addc_u32 s17, s35, 0
	s_cmp_lt_i32 s20, 6
	s_cselect_b64 s[0:1], -1, 0
	s_cmp_gt_i32 s21, 5
	s_cselect_b64 s[2:3], -1, 0
	s_and_b64 s[0:1], s[0:1], s[2:3]
	v_readlane_b32 s76, v254, 37
	v_readlane_b32 s68, v254, 41
	s_andn2_b64 vcc, exec, s[0:1]
	v_readlane_b32 s77, v254, 38
	v_readlane_b32 s69, v254, 42
	s_cbranch_vccnz .LBB0_940
	v_readlane_b32 s0, v255, 2
	s_waitcnt vmcnt(31)
	v_mbcnt_lo_u32_b32 v0, -1, 0
	v_mbcnt_hi_u32_b32 v0, -1, v0
	s_waitcnt vmcnt(24)
	v_or_b32_e32 v28, s0, v0
	v_readlane_b32 s0, v254, 15
	s_waitcnt vmcnt(16)
	s_nop 0
	v_lshl_add_u32 v62, s0, 9, v28
	v_mbcnt_lo_u32_b32 v0, -1, 0
	v_mbcnt_hi_u32_b32 v0, -1, v0
	s_add_u32 s54, s34, 0x47c00000
	s_addc_u32 s55, s35, 0
	v_readlane_b32 s0, v254, 15
	v_readlane_b32 s46, v255, 2
	s_nop 3
	s_lshl_b32 s0, s0, 9
	s_or_b32 s0, s0, s46
	s_add_u32 s56, s34, 0x2b500000
	s_addc_u32 s57, s35, 0
.Lp5_pool_outer:
	s_cmp_ge_u32 s0, 0x16800
	s_cbranch_scc1 .Lp5_pool_exit
	s_cmp_ge_u32 s0, 0x15800
	s_cbranch_scc1 .Lp5_pool_sample
	s_lshr_b32 s58, s0, 8
	s_and_b32 s60, s0, 0xff
	s_cmp_ge_u32 s58, 86
	s_cselect_b32 s59, 1, 0
	s_cmp_ge_u32 s58, 172
	s_cselect_b32 s46, 1, 0
	s_add_u32 s59, s59, s46
	s_cmp_ge_u32 s58, 258
	s_cselect_b32 s46, 1, 0
	s_add_u32 s59, s59, s46
	s_mul_i32 s46, s59, 86
	s_sub_u32 s58, s58, s46
	s_mul_i32 s1, s58, 24
	s_movk_i32 s2, 24
	s_mul_i32 s3, s59, 0x810
	s_mov_b32 s8, 1
	s_mov_b32 s9, 0
	s_mov_b64 s[52:53], 0
	s_branch .Lp5_pool_item
.Lp5_pool_sample:
	s_sub_u32 s46, s0, 0x15800
	s_and_b32 s60, s46, 0xff
	s_lshr_b32 s58, s46, 8
	s_lshr_b32 s59, s58, 1
	s_and_b32 s1, s58, 1
	s_lshl_b32 s1, s1, 4
	s_movk_i32 s2, 16
	s_lshl_b32 s3, s59, 5
	s_add_u32 s3, s3, 0x2040
	s_mov_b32 s8, 16
	s_mov_b32 s9, 1
	v_readlane_b32 s52, v255, 11
	v_readlane_b32 s53, v255, 12
	s_mul_i32 s46, s59, 0x1e000
	s_nop 1
	s_add_u32 s52, s52, s46
	s_addc_u32 s53, s53, 0
.Lp5_pool_item:
	s_lshr_b32 s46, s60, 6
	s_lshl_b32 s6, 2, s46
	s_sub_u32 s7, s6, 1
	s_lshl_b32 s46, s46, 23
	s_sub_u32 s10, 0x3f000000, s46
	v_add_u32_e32 v1, s60, v0
	v_lshlrev_b32_e32 v2, 5, v1
	v_lshlrev_b32_e32 v1, 4, v1
	v_mov_b32_e32 v16, 0
	v_mov_b32_e32 v17, 0
	v_mov_b32_e32 v18, 0
	v_mov_b32_e32 v19, 0
	v_mov_b32_e32 v20, 0
	v_mov_b32_e32 v21, 0
	v_mov_b32_e32 v22, 0
	v_mov_b32_e32 v23, 0
	s_mov_b32 s32, s1
	s_mov_b32 s61, 0
	s_add_u32 s46, s3, s1
	s_lshl_b32 s46, s46, 12
	s_add_u32 s42, s56, s46
	s_addc_u32 s43, s57, 0
.Lp5_pool_block:
	s_add_u32 s46, s3, s32
	s_mul_i32 s46, s46, 0x5000
	s_add_u32 s20, s54, s46
	s_addc_u32 s21, s55, 0
	global_load_dwordx4 v[64:67], v1, s[20:21]
	s_add_u32 s20, s20, 0x5000
	s_addc_u32 s21, s21, 0
	s_cmp_le_u32 s2, 1
	s_cbranch_scc1 .Lp5_pool_Edone
	global_load_dwordx4 v[68:71], v1, s[20:21]
	s_add_u32 s20, s20, 0x5000
	s_addc_u32 s21, s21, 0
	s_cmp_le_u32 s2, 2
	s_cbranch_scc1 .Lp5_pool_Edone
	global_load_dwordx4 v[72:75], v1, s[20:21]
	s_add_u32 s20, s20, 0x5000
	s_addc_u32 s21, s21, 0
	s_cmp_le_u32 s2, 3
	s_cbranch_scc1 .Lp5_pool_Edone
	global_load_dwordx4 v[76:79], v1, s[20:21]
	s_add_u32 s20, s20, 0x5000
	s_addc_u32 s21, s21, 0
	s_cmp_le_u32 s2, 4
	s_cbranch_scc1 .Lp5_pool_Edone
	global_load_dwordx4 v[80:83], v1, s[20:21]
	s_add_u32 s20, s20, 0x5000
	s_addc_u32 s21, s21, 0
	s_cmp_le_u32 s2, 5
	s_cbranch_scc1 .Lp5_pool_Edone
	global_load_dwordx4 v[84:87], v1, s[20:21]
	s_add_u32 s20, s20, 0x5000
	s_addc_u32 s21, s21, 0
	s_cmp_le_u32 s2, 6
	s_cbranch_scc1 .Lp5_pool_Edone
	global_load_dwordx4 v[88:91], v1, s[20:21]
	s_add_u32 s20, s20, 0x5000
	s_addc_u32 s21, s21, 0
	s_cmp_le_u32 s2, 7
	s_cbranch_scc1 .Lp5_pool_Edone
	global_load_dwordx4 v[92:95], v1, s[20:21]
	s_add_u32 s20, s20, 0x5000
	s_addc_u32 s21, s21, 0
	s_cmp_le_u32 s2, 8
	s_cbranch_scc1 .Lp5_pool_Edone
	global_load_dwordx4 v[96:99], v1, s[20:21]
	s_add_u32 s20, s20, 0x5000
	s_addc_u32 s21, s21, 0
	s_cmp_le_u32 s2, 9
	s_cbranch_scc1 .Lp5_pool_Edone
	global_load_dwordx4 v[100:103], v1, s[20:21]
	s_add_u32 s20, s20, 0x5000
	s_addc_u32 s21, s21, 0
	s_cmp_le_u32 s2, 10
	s_cbranch_scc1 .Lp5_pool_Edone
	global_load_dwordx4 v[104:107], v1, s[20:21]
	s_add_u32 s20, s20, 0x5000
	s_addc_u32 s21, s21, 0
	s_cmp_le_u32 s2, 11
	s_cbranch_scc1 .Lp5_pool_Edone
	global_load_dwordx4 v[108:111], v1, s[20:21]
	s_add_u32 s20, s20, 0x5000
	s_addc_u32 s21, s21, 0
	s_cmp_le_u32 s2, 12
	s_cbranch_scc1 .Lp5_pool_Edone
	global_load_dwordx4 v[112:115], v1, s[20:21]
	s_add_u32 s20, s20, 0x5000
	s_addc_u32 s21, s21, 0
	s_cmp_le_u32 s2, 13
	s_cbranch_scc1 .Lp5_pool_Edone
	global_load_dwordx4 v[116:119], v1, s[20:21]
	s_add_u32 s20, s20, 0x5000
	s_addc_u32 s21, s21, 0
	s_cmp_le_u32 s2, 14
	s_cbranch_scc1 .Lp5_pool_Edone
	global_load_dwordx4 v[120:123], v1, s[20:21]
	s_add_u32 s20, s20, 0x5000
	s_addc_u32 s21, s21, 0
	s_cmp_le_u32 s2, 15
	s_cbranch_scc1 .Lp5_pool_Edone
	global_load_dwordx4 v[124:127], v1, s[20:21]
	s_add_u32 s20, s20, 0x5000
	s_addc_u32 s21, s21, 0
.Lp5_pool_Edone:
	s_sub_i32 s29, s32, s7
	s_add_i32 s46, s3, s29
	s_mul_i32 s46, s46, 0x5000
	s_ashr_i32 s47, s46, 31
	s_add_u32 s22, s54, s46
	s_addc_u32 s23, s55, s47
	s_add_i32 s46, s29, 15
	s_lshl_b32 s46, s46, 13
	s_ashr_i32 s47, s46, 31
	s_add_u32 s30, s52, s46
	s_addc_u32 s31, s53, s47
	s_mov_b32 s66, s29
	s_cmp_lt_i32 s29, 0
	s_cbranch_scc1 .Lp5_pool_Lneg_0
	global_load_dwordx4 v[132:135], v1, s[22:23]
	s_branch .Lp5_pool_Lnext_0
.Lp5_pool_Lneg_0:
	s_cmp_eq_u32 s9, 0
	s_cbranch_scc1 .Lp5_pool_Lzero_0
	global_load_dwordx4 v[128:131], v2, s[30:31]
	global_load_dwordx4 v[132:135], v2, s[30:31] offset:16
	s_branch .Lp5_pool_Lnext_0
.Lp5_pool_Lzero_0:
	v_mov_b32_e32 v128, 0
	v_mov_b32_e32 v129, 0
	v_mov_b32_e32 v130, 0
	v_mov_b32_e32 v131, 0
	v_mov_b32_e32 v132, 0
	v_mov_b32_e32 v133, 0
	v_mov_b32_e32 v134, 0
	v_mov_b32_e32 v135, 0
.Lp5_pool_Lnext_0:
	s_add_u32 s22, s22, 0x5000
	s_addc_u32 s23, s23, 0
	s_add_u32 s30, s30, 0x2000
	s_addc_u32 s31, s31, 0
	s_add_i32 s29, s29, 1
	s_cmp_le_u32 s2, 1
	s_cbranch_scc1 .Lp5_pool_Ldone
	s_cmp_lt_i32 s29, 0
	s_cbranch_scc1 .Lp5_pool_Lneg_1
	global_load_dwordx4 v[140:143], v1, s[22:23]
	s_branch .Lp5_pool_Lnext_1
.Lp5_pool_Lneg_1:
	s_cmp_eq_u32 s9, 0
	s_cbranch_scc1 .Lp5_pool_Lzero_1
	global_load_dwordx4 v[136:139], v2, s[30:31]
	global_load_dwordx4 v[140:143], v2, s[30:31] offset:16
	s_branch .Lp5_pool_Lnext_1
.Lp5_pool_Lzero_1:
	v_mov_b32_e32 v136, 0
	v_mov_b32_e32 v137, 0
	v_mov_b32_e32 v138, 0
	v_mov_b32_e32 v139, 0
	v_mov_b32_e32 v140, 0
	v_mov_b32_e32 v141, 0
	v_mov_b32_e32 v142, 0
	v_mov_b32_e32 v143, 0
.Lp5_pool_Lnext_1:
	s_add_u32 s22, s22, 0x5000
	s_addc_u32 s23, s23, 0
	s_add_u32 s30, s30, 0x2000
	s_addc_u32 s31, s31, 0
	s_add_i32 s29, s29, 1
	s_cmp_le_u32 s2, 2
	s_cbranch_scc1 .Lp5_pool_Ldone
	s_cmp_lt_i32 s29, 0
	s_cbranch_scc1 .Lp5_pool_Lneg_2
	global_load_dwordx4 v[148:151], v1, s[22:23]
	s_branch .Lp5_pool_Lnext_2
.Lp5_pool_Lneg_2:
	s_cmp_eq_u32 s9, 0
	s_cbranch_scc1 .Lp5_pool_Lzero_2
	global_load_dwordx4 v[144:147], v2, s[30:31]
	global_load_dwordx4 v[148:151], v2, s[30:31] offset:16
	s_branch .Lp5_pool_Lnext_2
.Lp5_pool_Lzero_2:
	v_mov_b32_e32 v144, 0
	v_mov_b32_e32 v145, 0
	v_mov_b32_e32 v146, 0
	v_mov_b32_e32 v147, 0
	v_mov_b32_e32 v148, 0
	v_mov_b32_e32 v149, 0
	v_mov_b32_e32 v150, 0
	v_mov_b32_e32 v151, 0
.Lp5_pool_Lnext_2:
	s_add_u32 s22, s22, 0x5000
	s_addc_u32 s23, s23, 0
	s_add_u32 s30, s30, 0x2000
	s_addc_u32 s31, s31, 0
	s_add_i32 s29, s29, 1
	s_cmp_le_u32 s2, 3
	s_cbranch_scc1 .Lp5_pool_Ldone
	s_cmp_lt_i32 s29, 0
	s_cbranch_scc1 .Lp5_pool_Lneg_3
	global_load_dwordx4 v[156:159], v1, s[22:23]
	s_branch .Lp5_pool_Lnext_3
.Lp5_pool_Lneg_3:
	s_cmp_eq_u32 s9, 0
	s_cbranch_scc1 .Lp5_pool_Lzero_3
	global_load_dwordx4 v[152:155], v2, s[30:31]
	global_load_dwordx4 v[156:159], v2, s[30:31] offset:16
	s_branch .Lp5_pool_Lnext_3
.Lp5_pool_Lzero_3:
	v_mov_b32_e32 v152, 0
	v_mov_b32_e32 v153, 0
	v_mov_b32_e32 v154, 0
	v_mov_b32_e32 v155, 0
	v_mov_b32_e32 v156, 0
	v_mov_b32_e32 v157, 0
	v_mov_b32_e32 v158, 0
	v_mov_b32_e32 v159, 0
.Lp5_pool_Lnext_3:
	s_add_u32 s22, s22, 0x5000
	s_addc_u32 s23, s23, 0
	s_add_u32 s30, s30, 0x2000
	s_addc_u32 s31, s31, 0
	s_add_i32 s29, s29, 1
	s_cmp_le_u32 s2, 4
	s_cbranch_scc1 .Lp5_pool_Ldone
	s_cmp_lt_i32 s29, 0
	s_cbranch_scc1 .Lp5_pool_Lneg_4
	global_load_dwordx4 v[164:167], v1, s[22:23]
	s_branch .Lp5_pool_Lnext_4
.Lp5_pool_Lneg_4:
	s_cmp_eq_u32 s9, 0
	s_cbranch_scc1 .Lp5_pool_Lzero_4
	global_load_dwordx4 v[160:163], v2, s[30:31]
	global_load_dwordx4 v[164:167], v2, s[30:31] offset:16
	s_branch .Lp5_pool_Lnext_4
.Lp5_pool_Lzero_4:
	v_mov_b32_e32 v160, 0
	v_mov_b32_e32 v161, 0
	v_mov_b32_e32 v162, 0
	v_mov_b32_e32 v163, 0
	v_mov_b32_e32 v164, 0
	v_mov_b32_e32 v165, 0
	v_mov_b32_e32 v166, 0
	v_mov_b32_e32 v167, 0
.Lp5_pool_Lnext_4:
	s_add_u32 s22, s22, 0x5000
	s_addc_u32 s23, s23, 0
	s_add_u32 s30, s30, 0x2000
	s_addc_u32 s31, s31, 0
	s_add_i32 s29, s29, 1
	s_cmp_le_u32 s2, 5
	s_cbranch_scc1 .Lp5_pool_Ldone
	s_cmp_lt_i32 s29, 0
	s_cbranch_scc1 .Lp5_pool_Lneg_5
	global_load_dwordx4 v[172:175], v1, s[22:23]
	s_branch .Lp5_pool_Lnext_5
.Lp5_pool_Lneg_5:
	s_cmp_eq_u32 s9, 0
	s_cbranch_scc1 .Lp5_pool_Lzero_5
	global_load_dwordx4 v[168:171], v2, s[30:31]
	global_load_dwordx4 v[172:175], v2, s[30:31] offset:16
	s_branch .Lp5_pool_Lnext_5
.Lp5_pool_Lzero_5:
	v_mov_b32_e32 v168, 0
	v_mov_b32_e32 v169, 0
	v_mov_b32_e32 v170, 0
	v_mov_b32_e32 v171, 0
	v_mov_b32_e32 v172, 0
	v_mov_b32_e32 v173, 0
	v_mov_b32_e32 v174, 0
	v_mov_b32_e32 v175, 0
.Lp5_pool_Lnext_5:
	s_add_u32 s22, s22, 0x5000
	s_addc_u32 s23, s23, 0
	s_add_u32 s30, s30, 0x2000
	s_addc_u32 s31, s31, 0
	s_add_i32 s29, s29, 1
	s_cmp_le_u32 s2, 6
	s_cbranch_scc1 .Lp5_pool_Ldone
	s_cmp_lt_i32 s29, 0
	s_cbranch_scc1 .Lp5_pool_Lneg_6
	global_load_dwordx4 v[180:183], v1, s[22:23]
	s_branch .Lp5_pool_Lnext_6
.Lp5_pool_Lneg_6:
	s_cmp_eq_u32 s9, 0
	s_cbranch_scc1 .Lp5_pool_Lzero_6
	global_load_dwordx4 v[176:179], v2, s[30:31]
	global_load_dwordx4 v[180:183], v2, s[30:31] offset:16
	s_branch .Lp5_pool_Lnext_6
.Lp5_pool_Lzero_6:
	v_mov_b32_e32 v176, 0
	v_mov_b32_e32 v177, 0
	v_mov_b32_e32 v178, 0
	v_mov_b32_e32 v179, 0
	v_mov_b32_e32 v180, 0
	v_mov_b32_e32 v181, 0
	v_mov_b32_e32 v182, 0
	v_mov_b32_e32 v183, 0
.Lp5_pool_Lnext_6:
	s_add_u32 s22, s22, 0x5000
	s_addc_u32 s23, s23, 0
	s_add_u32 s30, s30, 0x2000
	s_addc_u32 s31, s31, 0
	s_add_i32 s29, s29, 1
	s_cmp_le_u32 s2, 7
	s_cbranch_scc1 .Lp5_pool_Ldone
	s_cmp_lt_i32 s29, 0
	s_cbranch_scc1 .Lp5_pool_Lneg_7
	global_load_dwordx4 v[188:191], v1, s[22:23]
	s_branch .Lp5_pool_Lnext_7
.Lp5_pool_Lneg_7:
	s_cmp_eq_u32 s9, 0
	s_cbranch_scc1 .Lp5_pool_Lzero_7
	global_load_dwordx4 v[184:187], v2, s[30:31]
	global_load_dwordx4 v[188:191], v2, s[30:31] offset:16
	s_branch .Lp5_pool_Lnext_7
.Lp5_pool_Lzero_7:
	v_mov_b32_e32 v184, 0
	v_mov_b32_e32 v185, 0
	v_mov_b32_e32 v186, 0
	v_mov_b32_e32 v187, 0
	v_mov_b32_e32 v188, 0
	v_mov_b32_e32 v189, 0
	v_mov_b32_e32 v190, 0
	v_mov_b32_e32 v191, 0
.Lp5_pool_Lnext_7:
	s_add_u32 s22, s22, 0x5000
	s_addc_u32 s23, s23, 0
	s_add_u32 s30, s30, 0x2000
	s_addc_u32 s31, s31, 0
	s_add_i32 s29, s29, 1
	s_cmp_le_u32 s2, 8
	s_cbranch_scc1 .Lp5_pool_Ldone
	s_cmp_lt_i32 s29, 0
	s_cbranch_scc1 .Lp5_pool_Lneg_8
	global_load_dwordx4 v[196:199], v1, s[22:23]
	s_branch .Lp5_pool_Lnext_8
.Lp5_pool_Lneg_8:
	s_cmp_eq_u32 s9, 0
	s_cbranch_scc1 .Lp5_pool_Lzero_8
	global_load_dwordx4 v[192:195], v2, s[30:31]
	global_load_dwordx4 v[196:199], v2, s[30:31] offset:16
	s_branch .Lp5_pool_Lnext_8
.Lp5_pool_Lzero_8:
	v_mov_b32_e32 v192, 0
	v_mov_b32_e32 v193, 0
	v_mov_b32_e32 v194, 0
	v_mov_b32_e32 v195, 0
	v_mov_b32_e32 v196, 0
	v_mov_b32_e32 v197, 0
	v_mov_b32_e32 v198, 0
	v_mov_b32_e32 v199, 0
.Lp5_pool_Lnext_8:
	s_add_u32 s22, s22, 0x5000
	s_addc_u32 s23, s23, 0
	s_add_u32 s30, s30, 0x2000
	s_addc_u32 s31, s31, 0
	s_add_i32 s29, s29, 1
	s_cmp_le_u32 s2, 9
	s_cbranch_scc1 .Lp5_pool_Ldone
	s_cmp_lt_i32 s29, 0
	s_cbranch_scc1 .Lp5_pool_Lneg_9
	global_load_dwordx4 v[204:207], v1, s[22:23]
	s_branch .Lp5_pool_Lnext_9
.Lp5_pool_Lneg_9:
	s_cmp_eq_u32 s9, 0
	s_cbranch_scc1 .Lp5_pool_Lzero_9
	global_load_dwordx4 v[200:203], v2, s[30:31]
	global_load_dwordx4 v[204:207], v2, s[30:31] offset:16
	s_branch .Lp5_pool_Lnext_9
.Lp5_pool_Lzero_9:
	v_mov_b32_e32 v200, 0
	v_mov_b32_e32 v201, 0
	v_mov_b32_e32 v202, 0
	v_mov_b32_e32 v203, 0
	v_mov_b32_e32 v204, 0
	v_mov_b32_e32 v205, 0
	v_mov_b32_e32 v206, 0
	v_mov_b32_e32 v207, 0
.Lp5_pool_Lnext_9:
	s_add_u32 s22, s22, 0x5000
	s_addc_u32 s23, s23, 0
	s_add_u32 s30, s30, 0x2000
	s_addc_u32 s31, s31, 0
	s_add_i32 s29, s29, 1
	s_cmp_le_u32 s2, 10
	s_cbranch_scc1 .Lp5_pool_Ldone
	s_cmp_lt_i32 s29, 0
	s_cbranch_scc1 .Lp5_pool_Lneg_10
	global_load_dwordx4 v[212:215], v1, s[22:23]
	s_branch .Lp5_pool_Lnext_10
.Lp5_pool_Lneg_10:
	s_cmp_eq_u32 s9, 0
	s_cbranch_scc1 .Lp5_pool_Lzero_10
	global_load_dwordx4 v[208:211], v2, s[30:31]
	global_load_dwordx4 v[212:215], v2, s[30:31] offset:16
	s_branch .Lp5_pool_Lnext_10
.Lp5_pool_Lzero_10:
	v_mov_b32_e32 v208, 0
	v_mov_b32_e32 v209, 0
	v_mov_b32_e32 v210, 0
	v_mov_b32_e32 v211, 0
	v_mov_b32_e32 v212, 0
	v_mov_b32_e32 v213, 0
	v_mov_b32_e32 v214, 0
	v_mov_b32_e32 v215, 0
.Lp5_pool_Lnext_10:
	s_add_u32 s22, s22, 0x5000
	s_addc_u32 s23, s23, 0
	s_add_u32 s30, s30, 0x2000
	s_addc_u32 s31, s31, 0
	s_add_i32 s29, s29, 1
	s_cmp_le_u32 s2, 11
	s_cbranch_scc1 .Lp5_pool_Ldone
	s_cmp_lt_i32 s29, 0
	s_cbranch_scc1 .Lp5_pool_Lneg_11
	global_load_dwordx4 v[220:223], v1, s[22:23]
	s_branch .Lp5_pool_Lnext_11
.Lp5_pool_Lneg_11:
	s_cmp_eq_u32 s9, 0
	s_cbranch_scc1 .Lp5_pool_Lzero_11
	global_load_dwordx4 v[216:219], v2, s[30:31]
	global_load_dwordx4 v[220:223], v2, s[30:31] offset:16
	s_branch .Lp5_pool_Lnext_11
.Lp5_pool_Lzero_11:
	v_mov_b32_e32 v216, 0
	v_mov_b32_e32 v217, 0
	v_mov_b32_e32 v218, 0
	v_mov_b32_e32 v219, 0
	v_mov_b32_e32 v220, 0
	v_mov_b32_e32 v221, 0
	v_mov_b32_e32 v222, 0
	v_mov_b32_e32 v223, 0
.Lp5_pool_Lnext_11:
	s_add_u32 s22, s22, 0x5000
	s_addc_u32 s23, s23, 0
	s_add_u32 s30, s30, 0x2000
	s_addc_u32 s31, s31, 0
	s_add_i32 s29, s29, 1
	s_cmp_le_u32 s2, 12
	s_cbranch_scc1 .Lp5_pool_Ldone
	s_cmp_lt_i32 s29, 0
	s_cbranch_scc1 .Lp5_pool_Lneg_12
	global_load_dwordx4 v[228:231], v1, s[22:23]
	s_branch .Lp5_pool_Lnext_12
.Lp5_pool_Lneg_12:
	s_cmp_eq_u32 s9, 0
	s_cbranch_scc1 .Lp5_pool_Lzero_12
	global_load_dwordx4 v[224:227], v2, s[30:31]
	global_load_dwordx4 v[228:231], v2, s[30:31] offset:16
	s_branch .Lp5_pool_Lnext_12
.Lp5_pool_Lzero_12:
	v_mov_b32_e32 v224, 0
	v_mov_b32_e32 v225, 0
	v_mov_b32_e32 v226, 0
	v_mov_b32_e32 v227, 0
	v_mov_b32_e32 v228, 0
	v_mov_b32_e32 v229, 0
	v_mov_b32_e32 v230, 0
	v_mov_b32_e32 v231, 0
.Lp5_pool_Lnext_12:
	s_add_u32 s22, s22, 0x5000
	s_addc_u32 s23, s23, 0
	s_add_u32 s30, s30, 0x2000
	s_addc_u32 s31, s31, 0
	s_add_i32 s29, s29, 1
	s_cmp_le_u32 s2, 13
	s_cbranch_scc1 .Lp5_pool_Ldone
	s_cmp_lt_i32 s29, 0
	s_cbranch_scc1 .Lp5_pool_Lneg_13
	global_load_dwordx4 v[236:239], v1, s[22:23]
	s_branch .Lp5_pool_Lnext_13
.Lp5_pool_Lneg_13:
	s_cmp_eq_u32 s9, 0
	s_cbranch_scc1 .Lp5_pool_Lzero_13
	global_load_dwordx4 v[232:235], v2, s[30:31]
	global_load_dwordx4 v[236:239], v2, s[30:31] offset:16
	s_branch .Lp5_pool_Lnext_13
.Lp5_pool_Lzero_13:
	v_mov_b32_e32 v232, 0
	v_mov_b32_e32 v233, 0
	v_mov_b32_e32 v234, 0
	v_mov_b32_e32 v235, 0
	v_mov_b32_e32 v236, 0
	v_mov_b32_e32 v237, 0
	v_mov_b32_e32 v238, 0
	v_mov_b32_e32 v239, 0
.Lp5_pool_Lnext_13:
	s_add_u32 s22, s22, 0x5000
	s_addc_u32 s23, s23, 0
	s_add_u32 s30, s30, 0x2000
	s_addc_u32 s31, s31, 0
	s_add_i32 s29, s29, 1
	s_cmp_le_u32 s2, 14
	s_cbranch_scc1 .Lp5_pool_Ldone
	s_cmp_lt_i32 s29, 0
	s_cbranch_scc1 .Lp5_pool_Lneg_14
	global_load_dwordx4 v[244:247], v1, s[22:23]
	s_branch .Lp5_pool_Lnext_14
.Lp5_pool_Lneg_14:
	s_cmp_eq_u32 s9, 0
	s_cbranch_scc1 .Lp5_pool_Lzero_14
	global_load_dwordx4 v[240:243], v2, s[30:31]
	global_load_dwordx4 v[244:247], v2, s[30:31] offset:16
	s_branch .Lp5_pool_Lnext_14
.Lp5_pool_Lzero_14:
	v_mov_b32_e32 v240, 0
	v_mov_b32_e32 v241, 0
	v_mov_b32_e32 v242, 0
	v_mov_b32_e32 v243, 0
	v_mov_b32_e32 v244, 0
	v_mov_b32_e32 v245, 0
	v_mov_b32_e32 v246, 0
	v_mov_b32_e32 v247, 0
.Lp5_pool_Lnext_14:
	s_add_u32 s22, s22, 0x5000
	s_addc_u32 s23, s23, 0
	s_add_u32 s30, s30, 0x2000
	s_addc_u32 s31, s31, 0
	s_add_i32 s29, s29, 1
	s_cmp_le_u32 s2, 15
	s_cbranch_scc1 .Lp5_pool_Ldone
	s_cmp_lt_i32 s29, 0
	s_cbranch_scc1 .Lp5_pool_Lneg_15
	global_load_dwordx4 v[52:55], v1, s[22:23]
	s_branch .Lp5_pool_Lnext_15
.Lp5_pool_Lneg_15:
	s_cmp_eq_u32 s9, 0
	s_cbranch_scc1 .Lp5_pool_Lzero_15
	global_load_dwordx4 v[48:51], v2, s[30:31]
	global_load_dwordx4 v[52:55], v2, s[30:31] offset:16
	s_branch .Lp5_pool_Lnext_15
.Lp5_pool_Lzero_15:
	v_mov_b32_e32 v48, 0
	v_mov_b32_e32 v49, 0
	v_mov_b32_e32 v50, 0
	v_mov_b32_e32 v51, 0
	v_mov_b32_e32 v52, 0
	v_mov_b32_e32 v53, 0
	v_mov_b32_e32 v54, 0
	v_mov_b32_e32 v55, 0
.Lp5_pool_Lnext_15:
	s_add_u32 s22, s22, 0x5000
	s_addc_u32 s23, s23, 0
	s_add_u32 s30, s30, 0x2000
	s_addc_u32 s31, s31, 0
	s_add_i32 s29, s29, 1
.Lp5_pool_Ldone:
	s_waitcnt vmcnt(0)
	s_mov_b32 s29, s66
	s_cmp_lt_i32 s29, 0
	s_cbranch_scc1 .Lp5_pool_Uskip_0
	v_lshlrev_b32_e32 v128, 16, v132
	v_and_b32_e32 v129, 0xffff0000, v132
	v_lshlrev_b32_e32 v130, 16, v133
	v_and_b32_e32 v131, 0xffff0000, v133
	v_lshlrev_b32_e32 v132, 16, v134
	v_and_b32_e32 v133, 0xffff0000, v134
	v_lshlrev_b32_e32 v134, 16, v135
	v_and_b32_e32 v135, 0xffff0000, v135
.Lp5_pool_Uskip_0:
	s_add_i32 s29, s29, 1
	s_cmp_le_u32 s2, 1
	s_cbranch_scc1 .Lp5_pool_Udone
	s_cmp_lt_i32 s29, 0
	s_cbranch_scc1 .Lp5_pool_Uskip_1
	v_lshlrev_b32_e32 v136, 16, v140
	v_and_b32_e32 v137, 0xffff0000, v140
	v_lshlrev_b32_e32 v138, 16, v141
	v_and_b32_e32 v139, 0xffff0000, v141
	v_lshlrev_b32_e32 v140, 16, v142
	v_and_b32_e32 v141, 0xffff0000, v142
	v_lshlrev_b32_e32 v142, 16, v143
	v_and_b32_e32 v143, 0xffff0000, v143
.Lp5_pool_Uskip_1:
	s_add_i32 s29, s29, 1
	s_cmp_le_u32 s2, 2
	s_cbranch_scc1 .Lp5_pool_Udone
	s_cmp_lt_i32 s29, 0
	s_cbranch_scc1 .Lp5_pool_Uskip_2
	v_lshlrev_b32_e32 v144, 16, v148
	v_and_b32_e32 v145, 0xffff0000, v148
	v_lshlrev_b32_e32 v146, 16, v149
	v_and_b32_e32 v147, 0xffff0000, v149
	v_lshlrev_b32_e32 v148, 16, v150
	v_and_b32_e32 v149, 0xffff0000, v150
	v_lshlrev_b32_e32 v150, 16, v151
	v_and_b32_e32 v151, 0xffff0000, v151
.Lp5_pool_Uskip_2:
	s_add_i32 s29, s29, 1
	s_cmp_le_u32 s2, 3
	s_cbranch_scc1 .Lp5_pool_Udone
	s_cmp_lt_i32 s29, 0
	s_cbranch_scc1 .Lp5_pool_Uskip_3
	v_lshlrev_b32_e32 v152, 16, v156
	v_and_b32_e32 v153, 0xffff0000, v156
	v_lshlrev_b32_e32 v154, 16, v157
	v_and_b32_e32 v155, 0xffff0000, v157
	v_lshlrev_b32_e32 v156, 16, v158
	v_and_b32_e32 v157, 0xffff0000, v158
	v_lshlrev_b32_e32 v158, 16, v159
	v_and_b32_e32 v159, 0xffff0000, v159
.Lp5_pool_Uskip_3:
	s_add_i32 s29, s29, 1
	s_cmp_le_u32 s2, 4
	s_cbranch_scc1 .Lp5_pool_Udone
	s_cmp_lt_i32 s29, 0
	s_cbranch_scc1 .Lp5_pool_Uskip_4
	v_lshlrev_b32_e32 v160, 16, v164
	v_and_b32_e32 v161, 0xffff0000, v164
	v_lshlrev_b32_e32 v162, 16, v165
	v_and_b32_e32 v163, 0xffff0000, v165
	v_lshlrev_b32_e32 v164, 16, v166
	v_and_b32_e32 v165, 0xffff0000, v166
	v_lshlrev_b32_e32 v166, 16, v167
	v_and_b32_e32 v167, 0xffff0000, v167
.Lp5_pool_Uskip_4:
	s_add_i32 s29, s29, 1
	s_cmp_le_u32 s2, 5
	s_cbranch_scc1 .Lp5_pool_Udone
	s_cmp_lt_i32 s29, 0
	s_cbranch_scc1 .Lp5_pool_Uskip_5
	v_lshlrev_b32_e32 v168, 16, v172
	v_and_b32_e32 v169, 0xffff0000, v172
	v_lshlrev_b32_e32 v170, 16, v173
	v_and_b32_e32 v171, 0xffff0000, v173
	v_lshlrev_b32_e32 v172, 16, v174
	v_and_b32_e32 v173, 0xffff0000, v174
	v_lshlrev_b32_e32 v174, 16, v175
	v_and_b32_e32 v175, 0xffff0000, v175
.Lp5_pool_Uskip_5:
	s_add_i32 s29, s29, 1
	s_cmp_le_u32 s2, 6
	s_cbranch_scc1 .Lp5_pool_Udone
	s_cmp_lt_i32 s29, 0
	s_cbranch_scc1 .Lp5_pool_Uskip_6
	v_lshlrev_b32_e32 v176, 16, v180
	v_and_b32_e32 v177, 0xffff0000, v180
	v_lshlrev_b32_e32 v178, 16, v181
	v_and_b32_e32 v179, 0xffff0000, v181
	v_lshlrev_b32_e32 v180, 16, v182
	v_and_b32_e32 v181, 0xffff0000, v182
	v_lshlrev_b32_e32 v182, 16, v183
	v_and_b32_e32 v183, 0xffff0000, v183
.Lp5_pool_Uskip_6:
	s_add_i32 s29, s29, 1
	s_cmp_le_u32 s2, 7
	s_cbranch_scc1 .Lp5_pool_Udone
	s_cmp_lt_i32 s29, 0
	s_cbranch_scc1 .Lp5_pool_Uskip_7
	v_lshlrev_b32_e32 v184, 16, v188
	v_and_b32_e32 v185, 0xffff0000, v188
	v_lshlrev_b32_e32 v186, 16, v189
	v_and_b32_e32 v187, 0xffff0000, v189
	v_lshlrev_b32_e32 v188, 16, v190
	v_and_b32_e32 v189, 0xffff0000, v190
	v_lshlrev_b32_e32 v190, 16, v191
	v_and_b32_e32 v191, 0xffff0000, v191
.Lp5_pool_Uskip_7:
	s_add_i32 s29, s29, 1
	s_cmp_le_u32 s2, 8
	s_cbranch_scc1 .Lp5_pool_Udone
	s_cmp_lt_i32 s29, 0
	s_cbranch_scc1 .Lp5_pool_Uskip_8
	v_lshlrev_b32_e32 v192, 16, v196
	v_and_b32_e32 v193, 0xffff0000, v196
	v_lshlrev_b32_e32 v194, 16, v197
	v_and_b32_e32 v195, 0xffff0000, v197
	v_lshlrev_b32_e32 v196, 16, v198
	v_and_b32_e32 v197, 0xffff0000, v198
	v_lshlrev_b32_e32 v198, 16, v199
	v_and_b32_e32 v199, 0xffff0000, v199
.Lp5_pool_Uskip_8:
	s_add_i32 s29, s29, 1
	s_cmp_le_u32 s2, 9
	s_cbranch_scc1 .Lp5_pool_Udone
	s_cmp_lt_i32 s29, 0
	s_cbranch_scc1 .Lp5_pool_Uskip_9
	v_lshlrev_b32_e32 v200, 16, v204
	v_and_b32_e32 v201, 0xffff0000, v204
	v_lshlrev_b32_e32 v202, 16, v205
	v_and_b32_e32 v203, 0xffff0000, v205
	v_lshlrev_b32_e32 v204, 16, v206
	v_and_b32_e32 v205, 0xffff0000, v206
	v_lshlrev_b32_e32 v206, 16, v207
	v_and_b32_e32 v207, 0xffff0000, v207
.Lp5_pool_Uskip_9:
	s_add_i32 s29, s29, 1
	s_cmp_le_u32 s2, 10
	s_cbranch_scc1 .Lp5_pool_Udone
	s_cmp_lt_i32 s29, 0
	s_cbranch_scc1 .Lp5_pool_Uskip_10
	v_lshlrev_b32_e32 v208, 16, v212
	v_and_b32_e32 v209, 0xffff0000, v212
	v_lshlrev_b32_e32 v210, 16, v213
	v_and_b32_e32 v211, 0xffff0000, v213
	v_lshlrev_b32_e32 v212, 16, v214
	v_and_b32_e32 v213, 0xffff0000, v214
	v_lshlrev_b32_e32 v214, 16, v215
	v_and_b32_e32 v215, 0xffff0000, v215
.Lp5_pool_Uskip_10:
	s_add_i32 s29, s29, 1
	s_cmp_le_u32 s2, 11
	s_cbranch_scc1 .Lp5_pool_Udone
	s_cmp_lt_i32 s29, 0
	s_cbranch_scc1 .Lp5_pool_Uskip_11
	v_lshlrev_b32_e32 v216, 16, v220
	v_and_b32_e32 v217, 0xffff0000, v220
	v_lshlrev_b32_e32 v218, 16, v221
	v_and_b32_e32 v219, 0xffff0000, v221
	v_lshlrev_b32_e32 v220, 16, v222
	v_and_b32_e32 v221, 0xffff0000, v222
	v_lshlrev_b32_e32 v222, 16, v223
	v_and_b32_e32 v223, 0xffff0000, v223
.Lp5_pool_Uskip_11:
	s_add_i32 s29, s29, 1
	s_cmp_le_u32 s2, 12
	s_cbranch_scc1 .Lp5_pool_Udone
	s_cmp_lt_i32 s29, 0
	s_cbranch_scc1 .Lp5_pool_Uskip_12
	v_lshlrev_b32_e32 v224, 16, v228
	v_and_b32_e32 v225, 0xffff0000, v228
	v_lshlrev_b32_e32 v226, 16, v229
	v_and_b32_e32 v227, 0xffff0000, v229
	v_lshlrev_b32_e32 v228, 16, v230
	v_and_b32_e32 v229, 0xffff0000, v230
	v_lshlrev_b32_e32 v230, 16, v231
	v_and_b32_e32 v231, 0xffff0000, v231
.Lp5_pool_Uskip_12:
	s_add_i32 s29, s29, 1
	s_cmp_le_u32 s2, 13
	s_cbranch_scc1 .Lp5_pool_Udone
	s_cmp_lt_i32 s29, 0
	s_cbranch_scc1 .Lp5_pool_Uskip_13
	v_lshlrev_b32_e32 v232, 16, v236
	v_and_b32_e32 v233, 0xffff0000, v236
	v_lshlrev_b32_e32 v234, 16, v237
	v_and_b32_e32 v235, 0xffff0000, v237
	v_lshlrev_b32_e32 v236, 16, v238
	v_and_b32_e32 v237, 0xffff0000, v238
	v_lshlrev_b32_e32 v238, 16, v239
	v_and_b32_e32 v239, 0xffff0000, v239
.Lp5_pool_Uskip_13:
	s_add_i32 s29, s29, 1
	s_cmp_le_u32 s2, 14
	s_cbranch_scc1 .Lp5_pool_Udone
	s_cmp_lt_i32 s29, 0
	s_cbranch_scc1 .Lp5_pool_Uskip_14
	v_lshlrev_b32_e32 v240, 16, v244
	v_and_b32_e32 v241, 0xffff0000, v244
	v_lshlrev_b32_e32 v242, 16, v245
	v_and_b32_e32 v243, 0xffff0000, v245
	v_lshlrev_b32_e32 v244, 16, v246
	v_and_b32_e32 v245, 0xffff0000, v246
	v_lshlrev_b32_e32 v246, 16, v247
	v_and_b32_e32 v247, 0xffff0000, v247
.Lp5_pool_Uskip_14:
	s_add_i32 s29, s29, 1
	s_cmp_le_u32 s2, 15
	s_cbranch_scc1 .Lp5_pool_Udone
	s_cmp_lt_i32 s29, 0
	s_cbranch_scc1 .Lp5_pool_Uskip_15
	v_lshlrev_b32_e32 v48, 16, v52
	v_and_b32_e32 v49, 0xffff0000, v52
	v_lshlrev_b32_e32 v50, 16, v53
	v_and_b32_e32 v51, 0xffff0000, v53
	v_lshlrev_b32_e32 v52, 16, v54
	v_and_b32_e32 v53, 0xffff0000, v54
	v_lshlrev_b32_e32 v54, 16, v55
	v_and_b32_e32 v55, 0xffff0000, v55
.Lp5_pool_Uskip_15:
	s_add_i32 s29, s29, 1
.Lp5_pool_Udone:
	s_cmp_lg_u32 s61, 0
	s_cbranch_scc1 .Lp5_pool_rows
	s_cmp_lt_u32 s7, 15
	s_cbranch_scc1 .Lp5_pool_pre_14
	v_pk_add_f32 v[16:17], v[16:17], v[240:241]
	v_pk_add_f32 v[18:19], v[18:19], v[242:243]
	v_pk_add_f32 v[20:21], v[20:21], v[244:245]
	v_pk_add_f32 v[22:23], v[22:23], v[246:247]
.Lp5_pool_pre_14:
	s_cmp_lt_u32 s7, 14
	s_cbranch_scc1 .Lp5_pool_pre_13
	v_pk_add_f32 v[16:17], v[16:17], v[232:233]
	v_pk_add_f32 v[18:19], v[18:19], v[234:235]
	v_pk_add_f32 v[20:21], v[20:21], v[236:237]
	v_pk_add_f32 v[22:23], v[22:23], v[238:239]
.Lp5_pool_pre_13:
	s_cmp_lt_u32 s7, 13
	s_cbranch_scc1 .Lp5_pool_pre_12
	v_pk_add_f32 v[16:17], v[16:17], v[224:225]
	v_pk_add_f32 v[18:19], v[18:19], v[226:227]
	v_pk_add_f32 v[20:21], v[20:21], v[228:229]
	v_pk_add_f32 v[22:23], v[22:23], v[230:231]
.Lp5_pool_pre_12:
	s_cmp_lt_u32 s7, 12
	s_cbranch_scc1 .Lp5_pool_pre_11
	v_pk_add_f32 v[16:17], v[16:17], v[216:217]
	v_pk_add_f32 v[18:19], v[18:19], v[218:219]
	v_pk_add_f32 v[20:21], v[20:21], v[220:221]
	v_pk_add_f32 v[22:23], v[22:23], v[222:223]
.Lp5_pool_pre_11:
	s_cmp_lt_u32 s7, 11
	s_cbranch_scc1 .Lp5_pool_pre_10
	v_pk_add_f32 v[16:17], v[16:17], v[208:209]
	v_pk_add_f32 v[18:19], v[18:19], v[210:211]
	v_pk_add_f32 v[20:21], v[20:21], v[212:213]
	v_pk_add_f32 v[22:23], v[22:23], v[214:215]
.Lp5_pool_pre_10:
	s_cmp_lt_u32 s7, 10
	s_cbranch_scc1 .Lp5_pool_pre_9
	v_pk_add_f32 v[16:17], v[16:17], v[200:201]
	v_pk_add_f32 v[18:19], v[18:19], v[202:203]
	v_pk_add_f32 v[20:21], v[20:21], v[204:205]
	v_pk_add_f32 v[22:23], v[22:23], v[206:207]
.Lp5_pool_pre_9:
	s_cmp_lt_u32 s7, 9
	s_cbranch_scc1 .Lp5_pool_pre_8
	v_pk_add_f32 v[16:17], v[16:17], v[192:193]
	v_pk_add_f32 v[18:19], v[18:19], v[194:195]
	v_pk_add_f32 v[20:21], v[20:21], v[196:197]
	v_pk_add_f32 v[22:23], v[22:23], v[198:199]
.Lp5_pool_pre_8:
	s_cmp_lt_u32 s7, 8
	s_cbranch_scc1 .Lp5_pool_pre_7
	v_pk_add_f32 v[16:17], v[16:17], v[184:185]
	v_pk_add_f32 v[18:19], v[18:19], v[186:187]
	v_pk_add_f32 v[20:21], v[20:21], v[188:189]
	v_pk_add_f32 v[22:23], v[22:23], v[190:191]
.Lp5_pool_pre_7:
	s_cmp_lt_u32 s7, 7
	s_cbranch_scc1 .Lp5_pool_pre_6
	v_pk_add_f32 v[16:17], v[16:17], v[176:177]
	v_pk_add_f32 v[18:19], v[18:19], v[178:179]
	v_pk_add_f32 v[20:21], v[20:21], v[180:181]
	v_pk_add_f32 v[22:23], v[22:23], v[182:183]
.Lp5_pool_pre_6:
	s_cmp_lt_u32 s7, 6
	s_cbranch_scc1 .Lp5_pool_pre_5
	v_pk_add_f32 v[16:17], v[16:17], v[168:169]
	v_pk_add_f32 v[18:19], v[18:19], v[170:171]
	v_pk_add_f32 v[20:21], v[20:21], v[172:173]
	v_pk_add_f32 v[22:23], v[22:23], v[174:175]
.Lp5_pool_pre_5:
	s_cmp_lt_u32 s7, 5
	s_cbranch_scc1 .Lp5_pool_pre_4
	v_pk_add_f32 v[16:17], v[16:17], v[160:161]
	v_pk_add_f32 v[18:19], v[18:19], v[162:163]
	v_pk_add_f32 v[20:21], v[20:21], v[164:165]
	v_pk_add_f32 v[22:23], v[22:23], v[166:167]
.Lp5_pool_pre_4:
	s_cmp_lt_u32 s7, 4
	s_cbranch_scc1 .Lp5_pool_pre_3
	v_pk_add_f32 v[16:17], v[16:17], v[152:153]
	v_pk_add_f32 v[18:19], v[18:19], v[154:155]
	v_pk_add_f32 v[20:21], v[20:21], v[156:157]
	v_pk_add_f32 v[22:23], v[22:23], v[158:159]
.Lp5_pool_pre_3:
	s_cmp_lt_u32 s7, 3
	s_cbranch_scc1 .Lp5_pool_pre_2
	v_pk_add_f32 v[16:17], v[16:17], v[144:145]
	v_pk_add_f32 v[18:19], v[18:19], v[146:147]
	v_pk_add_f32 v[20:21], v[20:21], v[148:149]
	v_pk_add_f32 v[22:23], v[22:23], v[150:151]
.Lp5_pool_pre_2:
	s_cmp_lt_u32 s7, 2
	s_cbranch_scc1 .Lp5_pool_pre_1
	v_pk_add_f32 v[16:17], v[16:17], v[136:137]
	v_pk_add_f32 v[18:19], v[18:19], v[138:139]
	v_pk_add_f32 v[20:21], v[20:21], v[140:141]
	v_pk_add_f32 v[22:23], v[22:23], v[142:143]
.Lp5_pool_pre_1:
	s_cmp_lt_u32 s7, 1
	s_cbranch_scc1 .Lp5_pool_pre_0
	v_pk_add_f32 v[16:17], v[16:17], v[128:129]
	v_pk_add_f32 v[18:19], v[18:19], v[130:131]
	v_pk_add_f32 v[20:21], v[20:21], v[132:133]
	v_pk_add_f32 v[22:23], v[22:23], v[134:135]
.Lp5_pool_pre_0:
.Lp5_pool_rows:
	s_cmp_eq_u32 s2, 0
	s_cbranch_scc1 .Lp5_pool_next_item
	s_add_u32 s67, s8, s32
	s_cmp_lt_u32 s67, s6
	s_cbranch_scc1 .Lp5_pool_div_0
	v_mov_b32_e32 v3, s10
	s_branch .Lp5_pool_inv_0
.Lp5_pool_div_0:
	v_cvt_f32_i32_e32 v4, s67
	v_div_scale_f32 v5, s[46:47], v4, v4, 1.0
	v_rcp_f32_e32 v6, v5
	s_nop 0
	v_fma_f32 v7, -v5, v6, 1.0
	v_fmac_f32_e32 v6, v7, v6
	v_div_scale_f32 v7, vcc, 1.0, v4, 1.0
	v_mul_f32_e32 v8, v7, v6
	v_fma_f32 v9, -v5, v8, v7
	v_fmac_f32_e32 v8, v9, v6
	v_fma_f32 v5, -v5, v8, v7
	s_nop 0
	v_div_fmas_f32 v5, v5, v6, v8
	v_div_fixup_f32 v3, v5, v4, 1.0
.Lp5_pool_inv_0:
	v_lshlrev_b32_e32 v24, 16, v64
	v_and_b32_e32 v25, 0xffff0000, v64
	v_lshlrev_b32_e32 v26, 16, v65
	v_and_b32_e32 v27, 0xffff0000, v65
	v_lshlrev_b32_e32 v28, 16, v66
	v_and_b32_e32 v29, 0xffff0000, v66
	v_lshlrev_b32_e32 v30, 16, v67
	v_and_b32_e32 v31, 0xffff0000, v67
	v_pk_add_f32 v[16:17], v[16:17], v[24:25]
	v_pk_add_f32 v[18:19], v[18:19], v[26:27]
	v_pk_add_f32 v[20:21], v[20:21], v[28:29]
	v_pk_add_f32 v[22:23], v[22:23], v[30:31]
	v_fma_f32 v32, v16, v3, -v24
	v_fma_f32 v33, v17, v3, -v25
	v_fma_f32 v34, v18, v3, -v26
	v_fma_f32 v35, v19, v3, -v27
	v_fma_f32 v36, v20, v3, -v28
	v_fma_f32 v37, v21, v3, -v29
	v_fma_f32 v38, v22, v3, -v30
	v_fma_f32 v39, v23, v3, -v31
	v_cvt_pk_bf16_f32 v40, v32, v33
	v_cvt_pk_bf16_f32 v41, v34, v35
	v_cvt_pk_bf16_f32 v42, v36, v37
	v_cvt_pk_bf16_f32 v43, v38, v39
	global_store_dwordx4 v1, v[40:43], s[42:43]
	v_pk_add_f32 v[16:17], v[16:17], v[128:129] neg_lo:[0,1] neg_hi:[0,1]
	v_pk_add_f32 v[18:19], v[18:19], v[130:131] neg_lo:[0,1] neg_hi:[0,1]
	v_pk_add_f32 v[20:21], v[20:21], v[132:133] neg_lo:[0,1] neg_hi:[0,1]
	v_pk_add_f32 v[22:23], v[22:23], v[134:135] neg_lo:[0,1] neg_hi:[0,1]
	s_add_u32 s42, s42, 0x1000
	s_addc_u32 s43, s43, 0
	s_add_u32 s32, s32, 1
	s_sub_u32 s2, s2, 1
	s_cmp_eq_u32 s2, 0
	s_cbranch_scc1 .Lp5_pool_next_item
	s_add_u32 s67, s8, s32
	s_cmp_lt_u32 s67, s6
	s_cbranch_scc1 .Lp5_pool_div_1
	v_mov_b32_e32 v3, s10
	s_branch .Lp5_pool_inv_1

.Lp5_pool_inv_1:
	v_lshlrev_b32_e32 v24, 16, v68
	v_and_b32_e32 v25, 0xffff0000, v68
	v_lshlrev_b32_e32 v26, 16, v69
	v_and_b32_e32 v27, 0xffff0000, v69
	v_lshlrev_b32_e32 v28, 16, v70
	v_and_b32_e32 v29, 0xffff0000, v70
	v_lshlrev_b32_e32 v30, 16, v71
	v_and_b32_e32 v31, 0xffff0000, v71
	v_pk_add_f32 v[16:17], v[16:17], v[24:25]
	v_pk_add_f32 v[18:19], v[18:19], v[26:27]
	v_pk_add_f32 v[20:21], v[20:21], v[28:29]
	v_pk_add_f32 v[22:23], v[22:23], v[30:31]
	v_fma_f32 v32, v16, v3, -v24
	v_fma_f32 v33, v17, v3, -v25
	v_fma_f32 v34, v18, v3, -v26
	v_fma_f32 v35, v19, v3, -v27
	v_fma_f32 v36, v20, v3, -v28
	v_fma_f32 v37, v21, v3, -v29
	v_fma_f32 v38, v22, v3, -v30
	v_fma_f32 v39, v23, v3, -v31
	v_cvt_pk_bf16_f32 v44, v32, v33
	v_cvt_pk_bf16_f32 v45, v34, v35
	v_cvt_pk_bf16_f32 v46, v36, v37
	v_cvt_pk_bf16_f32 v47, v38, v39
	global_store_dwordx4 v1, v[44:47], s[42:43]
	v_pk_add_f32 v[16:17], v[16:17], v[136:137] neg_lo:[0,1] neg_hi:[0,1]
	v_pk_add_f32 v[18:19], v[18:19], v[138:139] neg_lo:[0,1] neg_hi:[0,1]
	v_pk_add_f32 v[20:21], v[20:21], v[140:141] neg_lo:[0,1] neg_hi:[0,1]
	v_pk_add_f32 v[22:23], v[22:23], v[142:143] neg_lo:[0,1] neg_hi:[0,1]
	s_add_u32 s42, s42, 0x1000
	s_addc_u32 s43, s43, 0
	s_add_u32 s32, s32, 1
	s_sub_u32 s2, s2, 1
	s_cmp_eq_u32 s2, 0
	s_cbranch_scc1 .Lp5_pool_next_item
	s_add_u32 s67, s8, s32
	s_cmp_lt_u32 s67, s6
	s_cbranch_scc1 .Lp5_pool_div_2
	v_mov_b32_e32 v3, s10
	s_branch .Lp5_pool_inv_2

.Lp5_pool_inv_2:
	v_lshlrev_b32_e32 v24, 16, v72
	v_and_b32_e32 v25, 0xffff0000, v72
	v_lshlrev_b32_e32 v26, 16, v73
	v_and_b32_e32 v27, 0xffff0000, v73
	v_lshlrev_b32_e32 v28, 16, v74
	v_and_b32_e32 v29, 0xffff0000, v74
	v_lshlrev_b32_e32 v30, 16, v75
	v_and_b32_e32 v31, 0xffff0000, v75
	v_pk_add_f32 v[16:17], v[16:17], v[24:25]
	v_pk_add_f32 v[18:19], v[18:19], v[26:27]
	v_pk_add_f32 v[20:21], v[20:21], v[28:29]
	v_pk_add_f32 v[22:23], v[22:23], v[30:31]
	v_fma_f32 v32, v16, v3, -v24
	v_fma_f32 v33, v17, v3, -v25
	v_fma_f32 v34, v18, v3, -v26
	v_fma_f32 v35, v19, v3, -v27
	v_fma_f32 v36, v20, v3, -v28
	v_fma_f32 v37, v21, v3, -v29
	v_fma_f32 v38, v22, v3, -v30
	v_fma_f32 v39, v23, v3, -v31
	v_cvt_pk_bf16_f32 v40, v32, v33
	v_cvt_pk_bf16_f32 v41, v34, v35
	v_cvt_pk_bf16_f32 v42, v36, v37
	v_cvt_pk_bf16_f32 v43, v38, v39
	global_store_dwordx4 v1, v[40:43], s[42:43]
	v_pk_add_f32 v[16:17], v[16:17], v[144:145] neg_lo:[0,1] neg_hi:[0,1]
	v_pk_add_f32 v[18:19], v[18:19], v[146:147] neg_lo:[0,1] neg_hi:[0,1]
	v_pk_add_f32 v[20:21], v[20:21], v[148:149] neg_lo:[0,1] neg_hi:[0,1]
	v_pk_add_f32 v[22:23], v[22:23], v[150:151] neg_lo:[0,1] neg_hi:[0,1]
	s_add_u32 s42, s42, 0x1000
	s_addc_u32 s43, s43, 0
	s_add_u32 s32, s32, 1
	s_sub_u32 s2, s2, 1
	s_cmp_eq_u32 s2, 0
	s_cbranch_scc1 .Lp5_pool_next_item
	s_add_u32 s67, s8, s32
	s_cmp_lt_u32 s67, s6
	s_cbranch_scc1 .Lp5_pool_div_3
	v_mov_b32_e32 v3, s10
	s_branch .Lp5_pool_inv_3

.Lp5_pool_inv_3:
	v_lshlrev_b32_e32 v24, 16, v76
	v_and_b32_e32 v25, 0xffff0000, v76
	v_lshlrev_b32_e32 v26, 16, v77
	v_and_b32_e32 v27, 0xffff0000, v77
	v_lshlrev_b32_e32 v28, 16, v78
	v_and_b32_e32 v29, 0xffff0000, v78
	v_lshlrev_b32_e32 v30, 16, v79
	v_and_b32_e32 v31, 0xffff0000, v79
	v_pk_add_f32 v[16:17], v[16:17], v[24:25]
	v_pk_add_f32 v[18:19], v[18:19], v[26:27]
	v_pk_add_f32 v[20:21], v[20:21], v[28:29]
	v_pk_add_f32 v[22:23], v[22:23], v[30:31]
	v_fma_f32 v32, v16, v3, -v24
	v_fma_f32 v33, v17, v3, -v25
	v_fma_f32 v34, v18, v3, -v26
	v_fma_f32 v35, v19, v3, -v27
	v_fma_f32 v36, v20, v3, -v28
	v_fma_f32 v37, v21, v3, -v29
	v_fma_f32 v38, v22, v3, -v30
	v_fma_f32 v39, v23, v3, -v31
	v_cvt_pk_bf16_f32 v44, v32, v33
	v_cvt_pk_bf16_f32 v45, v34, v35
	v_cvt_pk_bf16_f32 v46, v36, v37
	v_cvt_pk_bf16_f32 v47, v38, v39
	global_store_dwordx4 v1, v[44:47], s[42:43]
	v_pk_add_f32 v[16:17], v[16:17], v[152:153] neg_lo:[0,1] neg_hi:[0,1]
	v_pk_add_f32 v[18:19], v[18:19], v[154:155] neg_lo:[0,1] neg_hi:[0,1]
	v_pk_add_f32 v[20:21], v[20:21], v[156:157] neg_lo:[0,1] neg_hi:[0,1]
	v_pk_add_f32 v[22:23], v[22:23], v[158:159] neg_lo:[0,1] neg_hi:[0,1]
	s_add_u32 s42, s42, 0x1000
	s_addc_u32 s43, s43, 0
	s_add_u32 s32, s32, 1
	s_sub_u32 s2, s2, 1
	s_cmp_eq_u32 s2, 0
	s_cbranch_scc1 .Lp5_pool_next_item
	s_add_u32 s67, s8, s32
	s_cmp_lt_u32 s67, s6
	s_cbranch_scc1 .Lp5_pool_div_4
	v_mov_b32_e32 v3, s10
	s_branch .Lp5_pool_inv_4

.Lp5_pool_inv_4:
	v_lshlrev_b32_e32 v24, 16, v80
	v_and_b32_e32 v25, 0xffff0000, v80
	v_lshlrev_b32_e32 v26, 16, v81
	v_and_b32_e32 v27, 0xffff0000, v81
	v_lshlrev_b32_e32 v28, 16, v82
	v_and_b32_e32 v29, 0xffff0000, v82
	v_lshlrev_b32_e32 v30, 16, v83
	v_and_b32_e32 v31, 0xffff0000, v83
	v_pk_add_f32 v[16:17], v[16:17], v[24:25]
	v_pk_add_f32 v[18:19], v[18:19], v[26:27]
	v_pk_add_f32 v[20:21], v[20:21], v[28:29]
	v_pk_add_f32 v[22:23], v[22:23], v[30:31]
	v_fma_f32 v32, v16, v3, -v24
	v_fma_f32 v33, v17, v3, -v25
	v_fma_f32 v34, v18, v3, -v26
	v_fma_f32 v35, v19, v3, -v27
	v_fma_f32 v36, v20, v3, -v28
	v_fma_f32 v37, v21, v3, -v29
	v_fma_f32 v38, v22, v3, -v30
	v_fma_f32 v39, v23, v3, -v31
	v_cvt_pk_bf16_f32 v40, v32, v33
	v_cvt_pk_bf16_f32 v41, v34, v35
	v_cvt_pk_bf16_f32 v42, v36, v37
	v_cvt_pk_bf16_f32 v43, v38, v39
	global_store_dwordx4 v1, v[40:43], s[42:43]
	v_pk_add_f32 v[16:17], v[16:17], v[160:161] neg_lo:[0,1] neg_hi:[0,1]
	v_pk_add_f32 v[18:19], v[18:19], v[162:163] neg_lo:[0,1] neg_hi:[0,1]
	v_pk_add_f32 v[20:21], v[20:21], v[164:165] neg_lo:[0,1] neg_hi:[0,1]
	v_pk_add_f32 v[22:23], v[22:23], v[166:167] neg_lo:[0,1] neg_hi:[0,1]
	s_add_u32 s42, s42, 0x1000
	s_addc_u32 s43, s43, 0
	s_add_u32 s32, s32, 1
	s_sub_u32 s2, s2, 1
	s_cmp_eq_u32 s2, 0
	s_cbranch_scc1 .Lp5_pool_next_item
	s_add_u32 s67, s8, s32
	s_cmp_lt_u32 s67, s6
	s_cbranch_scc1 .Lp5_pool_div_5
	v_mov_b32_e32 v3, s10
	s_branch .Lp5_pool_inv_5

.Lp5_pool_inv_5:
	v_lshlrev_b32_e32 v24, 16, v84
	v_and_b32_e32 v25, 0xffff0000, v84
	v_lshlrev_b32_e32 v26, 16, v85
	v_and_b32_e32 v27, 0xffff0000, v85
	v_lshlrev_b32_e32 v28, 16, v86
	v_and_b32_e32 v29, 0xffff0000, v86
	v_lshlrev_b32_e32 v30, 16, v87
	v_and_b32_e32 v31, 0xffff0000, v87
	v_pk_add_f32 v[16:17], v[16:17], v[24:25]
	v_pk_add_f32 v[18:19], v[18:19], v[26:27]
	v_pk_add_f32 v[20:21], v[20:21], v[28:29]
	v_pk_add_f32 v[22:23], v[22:23], v[30:31]
	v_fma_f32 v32, v16, v3, -v24
	v_fma_f32 v33, v17, v3, -v25
	v_fma_f32 v34, v18, v3, -v26
	v_fma_f32 v35, v19, v3, -v27
	v_fma_f32 v36, v20, v3, -v28
	v_fma_f32 v37, v21, v3, -v29
	v_fma_f32 v38, v22, v3, -v30
	v_fma_f32 v39, v23, v3, -v31
	v_cvt_pk_bf16_f32 v44, v32, v33
	v_cvt_pk_bf16_f32 v45, v34, v35
	v_cvt_pk_bf16_f32 v46, v36, v37
	v_cvt_pk_bf16_f32 v47, v38, v39
	global_store_dwordx4 v1, v[44:47], s[42:43]
	v_pk_add_f32 v[16:17], v[16:17], v[168:169] neg_lo:[0,1] neg_hi:[0,1]
	v_pk_add_f32 v[18:19], v[18:19], v[170:171] neg_lo:[0,1] neg_hi:[0,1]
	v_pk_add_f32 v[20:21], v[20:21], v[172:173] neg_lo:[0,1] neg_hi:[0,1]
	v_pk_add_f32 v[22:23], v[22:23], v[174:175] neg_lo:[0,1] neg_hi:[0,1]
	s_add_u32 s42, s42, 0x1000
	s_addc_u32 s43, s43, 0
	s_add_u32 s32, s32, 1
	s_sub_u32 s2, s2, 1
	s_cmp_eq_u32 s2, 0
	s_cbranch_scc1 .Lp5_pool_next_item
	s_add_u32 s67, s8, s32
	s_cmp_lt_u32 s67, s6
	s_cbranch_scc1 .Lp5_pool_div_6
	v_mov_b32_e32 v3, s10
	s_branch .Lp5_pool_inv_6

.Lp5_pool_inv_6:
	v_lshlrev_b32_e32 v24, 16, v88
	v_and_b32_e32 v25, 0xffff0000, v88
	v_lshlrev_b32_e32 v26, 16, v89
	v_and_b32_e32 v27, 0xffff0000, v89
	v_lshlrev_b32_e32 v28, 16, v90
	v_and_b32_e32 v29, 0xffff0000, v90
	v_lshlrev_b32_e32 v30, 16, v91
	v_and_b32_e32 v31, 0xffff0000, v91
	v_pk_add_f32 v[16:17], v[16:17], v[24:25]
	v_pk_add_f32 v[18:19], v[18:19], v[26:27]
	v_pk_add_f32 v[20:21], v[20:21], v[28:29]
	v_pk_add_f32 v[22:23], v[22:23], v[30:31]
	v_fma_f32 v32, v16, v3, -v24
	v_fma_f32 v33, v17, v3, -v25
	v_fma_f32 v34, v18, v3, -v26
	v_fma_f32 v35, v19, v3, -v27
	v_fma_f32 v36, v20, v3, -v28
	v_fma_f32 v37, v21, v3, -v29
	v_fma_f32 v38, v22, v3, -v30
	v_fma_f32 v39, v23, v3, -v31
	v_cvt_pk_bf16_f32 v40, v32, v33
	v_cvt_pk_bf16_f32 v41, v34, v35
	v_cvt_pk_bf16_f32 v42, v36, v37
	v_cvt_pk_bf16_f32 v43, v38, v39
	global_store_dwordx4 v1, v[40:43], s[42:43]
	v_pk_add_f32 v[16:17], v[16:17], v[176:177] neg_lo:[0,1] neg_hi:[0,1]
	v_pk_add_f32 v[18:19], v[18:19], v[178:179] neg_lo:[0,1] neg_hi:[0,1]
	v_pk_add_f32 v[20:21], v[20:21], v[180:181] neg_lo:[0,1] neg_hi:[0,1]
	v_pk_add_f32 v[22:23], v[22:23], v[182:183] neg_lo:[0,1] neg_hi:[0,1]
	s_add_u32 s42, s42, 0x1000
	s_addc_u32 s43, s43, 0
	s_add_u32 s32, s32, 1
	s_sub_u32 s2, s2, 1
	s_cmp_eq_u32 s2, 0
	s_cbranch_scc1 .Lp5_pool_next_item
	s_add_u32 s67, s8, s32
	s_cmp_lt_u32 s67, s6
	s_cbranch_scc1 .Lp5_pool_div_7
	v_mov_b32_e32 v3, s10
	s_branch .Lp5_pool_inv_7

.Lp5_pool_inv_7:
	v_lshlrev_b32_e32 v24, 16, v92
	v_and_b32_e32 v25, 0xffff0000, v92
	v_lshlrev_b32_e32 v26, 16, v93
	v_and_b32_e32 v27, 0xffff0000, v93
	v_lshlrev_b32_e32 v28, 16, v94
	v_and_b32_e32 v29, 0xffff0000, v94
	v_lshlrev_b32_e32 v30, 16, v95
	v_and_b32_e32 v31, 0xffff0000, v95
	v_pk_add_f32 v[16:17], v[16:17], v[24:25]
	v_pk_add_f32 v[18:19], v[18:19], v[26:27]
	v_pk_add_f32 v[20:21], v[20:21], v[28:29]
	v_pk_add_f32 v[22:23], v[22:23], v[30:31]
	v_fma_f32 v32, v16, v3, -v24
	v_fma_f32 v33, v17, v3, -v25
	v_fma_f32 v34, v18, v3, -v26
	v_fma_f32 v35, v19, v3, -v27
	v_fma_f32 v36, v20, v3, -v28
	v_fma_f32 v37, v21, v3, -v29
	v_fma_f32 v38, v22, v3, -v30
	v_fma_f32 v39, v23, v3, -v31
	v_cvt_pk_bf16_f32 v44, v32, v33
	v_cvt_pk_bf16_f32 v45, v34, v35
	v_cvt_pk_bf16_f32 v46, v36, v37
	v_cvt_pk_bf16_f32 v47, v38, v39
	global_store_dwordx4 v1, v[44:47], s[42:43]
	v_pk_add_f32 v[16:17], v[16:17], v[184:185] neg_lo:[0,1] neg_hi:[0,1]
	v_pk_add_f32 v[18:19], v[18:19], v[186:187] neg_lo:[0,1] neg_hi:[0,1]
	v_pk_add_f32 v[20:21], v[20:21], v[188:189] neg_lo:[0,1] neg_hi:[0,1]
	v_pk_add_f32 v[22:23], v[22:23], v[190:191] neg_lo:[0,1] neg_hi:[0,1]
	s_add_u32 s42, s42, 0x1000
	s_addc_u32 s43, s43, 0
	s_add_u32 s32, s32, 1
	s_sub_u32 s2, s2, 1
	s_cmp_eq_u32 s2, 0
	s_cbranch_scc1 .Lp5_pool_next_item
	s_add_u32 s67, s8, s32
	s_cmp_lt_u32 s67, s6
	s_cbranch_scc1 .Lp5_pool_div_8
	v_mov_b32_e32 v3, s10
	s_branch .Lp5_pool_inv_8

.Lp5_pool_inv_8:
	v_lshlrev_b32_e32 v24, 16, v96
	v_and_b32_e32 v25, 0xffff0000, v96
	v_lshlrev_b32_e32 v26, 16, v97
	v_and_b32_e32 v27, 0xffff0000, v97
	v_lshlrev_b32_e32 v28, 16, v98
	v_and_b32_e32 v29, 0xffff0000, v98
	v_lshlrev_b32_e32 v30, 16, v99
	v_and_b32_e32 v31, 0xffff0000, v99
	v_pk_add_f32 v[16:17], v[16:17], v[24:25]
	v_pk_add_f32 v[18:19], v[18:19], v[26:27]
	v_pk_add_f32 v[20:21], v[20:21], v[28:29]
	v_pk_add_f32 v[22:23], v[22:23], v[30:31]
	v_fma_f32 v32, v16, v3, -v24
	v_fma_f32 v33, v17, v3, -v25
	v_fma_f32 v34, v18, v3, -v26
	v_fma_f32 v35, v19, v3, -v27
	v_fma_f32 v36, v20, v3, -v28
	v_fma_f32 v37, v21, v3, -v29
	v_fma_f32 v38, v22, v3, -v30
	v_fma_f32 v39, v23, v3, -v31
	v_cvt_pk_bf16_f32 v40, v32, v33
	v_cvt_pk_bf16_f32 v41, v34, v35
	v_cvt_pk_bf16_f32 v42, v36, v37
	v_cvt_pk_bf16_f32 v43, v38, v39
	global_store_dwordx4 v1, v[40:43], s[42:43]
	v_pk_add_f32 v[16:17], v[16:17], v[192:193] neg_lo:[0,1] neg_hi:[0,1]
	v_pk_add_f32 v[18:19], v[18:19], v[194:195] neg_lo:[0,1] neg_hi:[0,1]
	v_pk_add_f32 v[20:21], v[20:21], v[196:197] neg_lo:[0,1] neg_hi:[0,1]
	v_pk_add_f32 v[22:23], v[22:23], v[198:199] neg_lo:[0,1] neg_hi:[0,1]
	s_add_u32 s42, s42, 0x1000
	s_addc_u32 s43, s43, 0
	s_add_u32 s32, s32, 1
	s_sub_u32 s2, s2, 1
	s_cmp_eq_u32 s2, 0
	s_cbranch_scc1 .Lp5_pool_next_item
	s_add_u32 s67, s8, s32
	s_cmp_lt_u32 s67, s6
	s_cbranch_scc1 .Lp5_pool_div_9
	v_mov_b32_e32 v3, s10
	s_branch .Lp5_pool_inv_9

.Lp5_pool_inv_9:
	v_lshlrev_b32_e32 v24, 16, v100
	v_and_b32_e32 v25, 0xffff0000, v100
	v_lshlrev_b32_e32 v26, 16, v101
	v_and_b32_e32 v27, 0xffff0000, v101
	v_lshlrev_b32_e32 v28, 16, v102
	v_and_b32_e32 v29, 0xffff0000, v102
	v_lshlrev_b32_e32 v30, 16, v103
	v_and_b32_e32 v31, 0xffff0000, v103
	v_pk_add_f32 v[16:17], v[16:17], v[24:25]
	v_pk_add_f32 v[18:19], v[18:19], v[26:27]
	v_pk_add_f32 v[20:21], v[20:21], v[28:29]
	v_pk_add_f32 v[22:23], v[22:23], v[30:31]
	v_fma_f32 v32, v16, v3, -v24
	v_fma_f32 v33, v17, v3, -v25
	v_fma_f32 v34, v18, v3, -v26
	v_fma_f32 v35, v19, v3, -v27
	v_fma_f32 v36, v20, v3, -v28
	v_fma_f32 v37, v21, v3, -v29
	v_fma_f32 v38, v22, v3, -v30
	v_fma_f32 v39, v23, v3, -v31
	v_cvt_pk_bf16_f32 v44, v32, v33
	v_cvt_pk_bf16_f32 v45, v34, v35
	v_cvt_pk_bf16_f32 v46, v36, v37
	v_cvt_pk_bf16_f32 v47, v38, v39
	global_store_dwordx4 v1, v[44:47], s[42:43]
	v_pk_add_f32 v[16:17], v[16:17], v[200:201] neg_lo:[0,1] neg_hi:[0,1]
	v_pk_add_f32 v[18:19], v[18:19], v[202:203] neg_lo:[0,1] neg_hi:[0,1]
	v_pk_add_f32 v[20:21], v[20:21], v[204:205] neg_lo:[0,1] neg_hi:[0,1]
	v_pk_add_f32 v[22:23], v[22:23], v[206:207] neg_lo:[0,1] neg_hi:[0,1]
	s_add_u32 s42, s42, 0x1000
	s_addc_u32 s43, s43, 0
	s_add_u32 s32, s32, 1
	s_sub_u32 s2, s2, 1
	s_cmp_eq_u32 s2, 0
	s_cbranch_scc1 .Lp5_pool_next_item
	s_add_u32 s67, s8, s32
	s_cmp_lt_u32 s67, s6
	s_cbranch_scc1 .Lp5_pool_div_10
	v_mov_b32_e32 v3, s10
	s_branch .Lp5_pool_inv_10

.Lp5_pool_inv_10:
	v_lshlrev_b32_e32 v24, 16, v104
	v_and_b32_e32 v25, 0xffff0000, v104
	v_lshlrev_b32_e32 v26, 16, v105
	v_and_b32_e32 v27, 0xffff0000, v105
	v_lshlrev_b32_e32 v28, 16, v106
	v_and_b32_e32 v29, 0xffff0000, v106
	v_lshlrev_b32_e32 v30, 16, v107
	v_and_b32_e32 v31, 0xffff0000, v107
	v_pk_add_f32 v[16:17], v[16:17], v[24:25]
	v_pk_add_f32 v[18:19], v[18:19], v[26:27]
	v_pk_add_f32 v[20:21], v[20:21], v[28:29]
	v_pk_add_f32 v[22:23], v[22:23], v[30:31]
	v_fma_f32 v32, v16, v3, -v24
	v_fma_f32 v33, v17, v3, -v25
	v_fma_f32 v34, v18, v3, -v26
	v_fma_f32 v35, v19, v3, -v27
	v_fma_f32 v36, v20, v3, -v28
	v_fma_f32 v37, v21, v3, -v29
	v_fma_f32 v38, v22, v3, -v30
	v_fma_f32 v39, v23, v3, -v31
	v_cvt_pk_bf16_f32 v40, v32, v33
	v_cvt_pk_bf16_f32 v41, v34, v35
	v_cvt_pk_bf16_f32 v42, v36, v37
	v_cvt_pk_bf16_f32 v43, v38, v39
	global_store_dwordx4 v1, v[40:43], s[42:43]
	v_pk_add_f32 v[16:17], v[16:17], v[208:209] neg_lo:[0,1] neg_hi:[0,1]
	v_pk_add_f32 v[18:19], v[18:19], v[210:211] neg_lo:[0,1] neg_hi:[0,1]
	v_pk_add_f32 v[20:21], v[20:21], v[212:213] neg_lo:[0,1] neg_hi:[0,1]
	v_pk_add_f32 v[22:23], v[22:23], v[214:215] neg_lo:[0,1] neg_hi:[0,1]
	s_add_u32 s42, s42, 0x1000
	s_addc_u32 s43, s43, 0
	s_add_u32 s32, s32, 1
	s_sub_u32 s2, s2, 1
	s_cmp_eq_u32 s2, 0
	s_cbranch_scc1 .Lp5_pool_next_item
	s_add_u32 s67, s8, s32
	s_cmp_lt_u32 s67, s6
	s_cbranch_scc1 .Lp5_pool_div_11
	v_mov_b32_e32 v3, s10
	s_branch .Lp5_pool_inv_11

.Lp5_pool_inv_11:
	v_lshlrev_b32_e32 v24, 16, v108
	v_and_b32_e32 v25, 0xffff0000, v108
	v_lshlrev_b32_e32 v26, 16, v109
	v_and_b32_e32 v27, 0xffff0000, v109
	v_lshlrev_b32_e32 v28, 16, v110
	v_and_b32_e32 v29, 0xffff0000, v110
	v_lshlrev_b32_e32 v30, 16, v111
	v_and_b32_e32 v31, 0xffff0000, v111
	v_pk_add_f32 v[16:17], v[16:17], v[24:25]
	v_pk_add_f32 v[18:19], v[18:19], v[26:27]
	v_pk_add_f32 v[20:21], v[20:21], v[28:29]
	v_pk_add_f32 v[22:23], v[22:23], v[30:31]
	v_fma_f32 v32, v16, v3, -v24
	v_fma_f32 v33, v17, v3, -v25
	v_fma_f32 v34, v18, v3, -v26
	v_fma_f32 v35, v19, v3, -v27
	v_fma_f32 v36, v20, v3, -v28
	v_fma_f32 v37, v21, v3, -v29
	v_fma_f32 v38, v22, v3, -v30
	v_fma_f32 v39, v23, v3, -v31
	v_cvt_pk_bf16_f32 v44, v32, v33
	v_cvt_pk_bf16_f32 v45, v34, v35
	v_cvt_pk_bf16_f32 v46, v36, v37
	v_cvt_pk_bf16_f32 v47, v38, v39
	global_store_dwordx4 v1, v[44:47], s[42:43]
	v_pk_add_f32 v[16:17], v[16:17], v[216:217] neg_lo:[0,1] neg_hi:[0,1]
	v_pk_add_f32 v[18:19], v[18:19], v[218:219] neg_lo:[0,1] neg_hi:[0,1]
	v_pk_add_f32 v[20:21], v[20:21], v[220:221] neg_lo:[0,1] neg_hi:[0,1]
	v_pk_add_f32 v[22:23], v[22:23], v[222:223] neg_lo:[0,1] neg_hi:[0,1]
	s_add_u32 s42, s42, 0x1000
	s_addc_u32 s43, s43, 0
	s_add_u32 s32, s32, 1
	s_sub_u32 s2, s2, 1
	s_cmp_eq_u32 s2, 0
	s_cbranch_scc1 .Lp5_pool_next_item
	s_add_u32 s67, s8, s32
	s_cmp_lt_u32 s67, s6
	s_cbranch_scc1 .Lp5_pool_div_12
	v_mov_b32_e32 v3, s10
	s_branch .Lp5_pool_inv_12

.Lp5_pool_inv_12:
	v_lshlrev_b32_e32 v24, 16, v112
	v_and_b32_e32 v25, 0xffff0000, v112
	v_lshlrev_b32_e32 v26, 16, v113
	v_and_b32_e32 v27, 0xffff0000, v113
	v_lshlrev_b32_e32 v28, 16, v114
	v_and_b32_e32 v29, 0xffff0000, v114
	v_lshlrev_b32_e32 v30, 16, v115
	v_and_b32_e32 v31, 0xffff0000, v115
	v_pk_add_f32 v[16:17], v[16:17], v[24:25]
	v_pk_add_f32 v[18:19], v[18:19], v[26:27]
	v_pk_add_f32 v[20:21], v[20:21], v[28:29]
	v_pk_add_f32 v[22:23], v[22:23], v[30:31]
	v_fma_f32 v32, v16, v3, -v24
	v_fma_f32 v33, v17, v3, -v25
	v_fma_f32 v34, v18, v3, -v26
	v_fma_f32 v35, v19, v3, -v27
	v_fma_f32 v36, v20, v3, -v28
	v_fma_f32 v37, v21, v3, -v29
	v_fma_f32 v38, v22, v3, -v30
	v_fma_f32 v39, v23, v3, -v31
	v_cvt_pk_bf16_f32 v40, v32, v33
	v_cvt_pk_bf16_f32 v41, v34, v35
	v_cvt_pk_bf16_f32 v42, v36, v37
	v_cvt_pk_bf16_f32 v43, v38, v39
	global_store_dwordx4 v1, v[40:43], s[42:43]
	v_pk_add_f32 v[16:17], v[16:17], v[224:225] neg_lo:[0,1] neg_hi:[0,1]
	v_pk_add_f32 v[18:19], v[18:19], v[226:227] neg_lo:[0,1] neg_hi:[0,1]
	v_pk_add_f32 v[20:21], v[20:21], v[228:229] neg_lo:[0,1] neg_hi:[0,1]
	v_pk_add_f32 v[22:23], v[22:23], v[230:231] neg_lo:[0,1] neg_hi:[0,1]
	s_add_u32 s42, s42, 0x1000
	s_addc_u32 s43, s43, 0
	s_add_u32 s32, s32, 1
	s_sub_u32 s2, s2, 1
	s_cmp_eq_u32 s2, 0
	s_cbranch_scc1 .Lp5_pool_next_item
	s_add_u32 s67, s8, s32
	s_cmp_lt_u32 s67, s6
	s_cbranch_scc1 .Lp5_pool_div_13
	v_mov_b32_e32 v3, s10
	s_branch .Lp5_pool_inv_13

.Lp5_pool_inv_13:
	v_lshlrev_b32_e32 v24, 16, v116
	v_and_b32_e32 v25, 0xffff0000, v116
	v_lshlrev_b32_e32 v26, 16, v117
	v_and_b32_e32 v27, 0xffff0000, v117
	v_lshlrev_b32_e32 v28, 16, v118
	v_and_b32_e32 v29, 0xffff0000, v118
	v_lshlrev_b32_e32 v30, 16, v119
	v_and_b32_e32 v31, 0xffff0000, v119
	v_pk_add_f32 v[16:17], v[16:17], v[24:25]
	v_pk_add_f32 v[18:19], v[18:19], v[26:27]
	v_pk_add_f32 v[20:21], v[20:21], v[28:29]
	v_pk_add_f32 v[22:23], v[22:23], v[30:31]
	v_fma_f32 v32, v16, v3, -v24
	v_fma_f32 v33, v17, v3, -v25
	v_fma_f32 v34, v18, v3, -v26
	v_fma_f32 v35, v19, v3, -v27
	v_fma_f32 v36, v20, v3, -v28
	v_fma_f32 v37, v21, v3, -v29
	v_fma_f32 v38, v22, v3, -v30
	v_fma_f32 v39, v23, v3, -v31
	v_cvt_pk_bf16_f32 v44, v32, v33
	v_cvt_pk_bf16_f32 v45, v34, v35
	v_cvt_pk_bf16_f32 v46, v36, v37
	v_cvt_pk_bf16_f32 v47, v38, v39
	global_store_dwordx4 v1, v[44:47], s[42:43]
	v_pk_add_f32 v[16:17], v[16:17], v[232:233] neg_lo:[0,1] neg_hi:[0,1]
	v_pk_add_f32 v[18:19], v[18:19], v[234:235] neg_lo:[0,1] neg_hi:[0,1]
	v_pk_add_f32 v[20:21], v[20:21], v[236:237] neg_lo:[0,1] neg_hi:[0,1]
	v_pk_add_f32 v[22:23], v[22:23], v[238:239] neg_lo:[0,1] neg_hi:[0,1]
	s_add_u32 s42, s42, 0x1000
	s_addc_u32 s43, s43, 0
	s_add_u32 s32, s32, 1
	s_sub_u32 s2, s2, 1
	s_cmp_eq_u32 s2, 0
	s_cbranch_scc1 .Lp5_pool_next_item
	s_add_u32 s67, s8, s32
	s_cmp_lt_u32 s67, s6
	s_cbranch_scc1 .Lp5_pool_div_14
	v_mov_b32_e32 v3, s10
	s_branch .Lp5_pool_inv_14

.Lp5_pool_inv_14:
	v_lshlrev_b32_e32 v24, 16, v120
	v_and_b32_e32 v25, 0xffff0000, v120
	v_lshlrev_b32_e32 v26, 16, v121
	v_and_b32_e32 v27, 0xffff0000, v121
	v_lshlrev_b32_e32 v28, 16, v122
	v_and_b32_e32 v29, 0xffff0000, v122
	v_lshlrev_b32_e32 v30, 16, v123
	v_and_b32_e32 v31, 0xffff0000, v123
	v_pk_add_f32 v[16:17], v[16:17], v[24:25]
	v_pk_add_f32 v[18:19], v[18:19], v[26:27]
	v_pk_add_f32 v[20:21], v[20:21], v[28:29]
	v_pk_add_f32 v[22:23], v[22:23], v[30:31]
	v_fma_f32 v32, v16, v3, -v24
	v_fma_f32 v33, v17, v3, -v25
	v_fma_f32 v34, v18, v3, -v26
	v_fma_f32 v35, v19, v3, -v27
	v_fma_f32 v36, v20, v3, -v28
	v_fma_f32 v37, v21, v3, -v29
	v_fma_f32 v38, v22, v3, -v30
	v_fma_f32 v39, v23, v3, -v31
	v_cvt_pk_bf16_f32 v40, v32, v33
	v_cvt_pk_bf16_f32 v41, v34, v35
	v_cvt_pk_bf16_f32 v42, v36, v37
	v_cvt_pk_bf16_f32 v43, v38, v39
	global_store_dwordx4 v1, v[40:43], s[42:43]
	v_pk_add_f32 v[16:17], v[16:17], v[240:241] neg_lo:[0,1] neg_hi:[0,1]
	v_pk_add_f32 v[18:19], v[18:19], v[242:243] neg_lo:[0,1] neg_hi:[0,1]
	v_pk_add_f32 v[20:21], v[20:21], v[244:245] neg_lo:[0,1] neg_hi:[0,1]
	v_pk_add_f32 v[22:23], v[22:23], v[246:247] neg_lo:[0,1] neg_hi:[0,1]
	s_add_u32 s42, s42, 0x1000
	s_addc_u32 s43, s43, 0
	s_add_u32 s32, s32, 1
	s_sub_u32 s2, s2, 1
	s_cmp_eq_u32 s2, 0
	s_cbranch_scc1 .Lp5_pool_next_item
	s_add_u32 s67, s8, s32
	s_cmp_lt_u32 s67, s6
	s_cbranch_scc1 .Lp5_pool_div_15
	v_mov_b32_e32 v3, s10
	s_branch .Lp5_pool_inv_15

.Lp5_pool_inv_15:
	v_lshlrev_b32_e32 v24, 16, v124
	v_and_b32_e32 v25, 0xffff0000, v124
	v_lshlrev_b32_e32 v26, 16, v125
	v_and_b32_e32 v27, 0xffff0000, v125
	v_lshlrev_b32_e32 v28, 16, v126
	v_and_b32_e32 v29, 0xffff0000, v126
	v_lshlrev_b32_e32 v30, 16, v127
	v_and_b32_e32 v31, 0xffff0000, v127
	v_pk_add_f32 v[16:17], v[16:17], v[24:25]
	v_pk_add_f32 v[18:19], v[18:19], v[26:27]
	v_pk_add_f32 v[20:21], v[20:21], v[28:29]
	v_pk_add_f32 v[22:23], v[22:23], v[30:31]
	v_fma_f32 v32, v16, v3, -v24
	v_fma_f32 v33, v17, v3, -v25
	v_fma_f32 v34, v18, v3, -v26
	v_fma_f32 v35, v19, v3, -v27
	v_fma_f32 v36, v20, v3, -v28
	v_fma_f32 v37, v21, v3, -v29
	v_fma_f32 v38, v22, v3, -v30
	v_fma_f32 v39, v23, v3, -v31
	v_cvt_pk_bf16_f32 v44, v32, v33
	v_cvt_pk_bf16_f32 v45, v34, v35
	v_cvt_pk_bf16_f32 v46, v36, v37
	v_cvt_pk_bf16_f32 v47, v38, v39
	global_store_dwordx4 v1, v[44:47], s[42:43]
	v_pk_add_f32 v[16:17], v[16:17], v[48:49] neg_lo:[0,1] neg_hi:[0,1]
	v_pk_add_f32 v[18:19], v[18:19], v[50:51] neg_lo:[0,1] neg_hi:[0,1]
	v_pk_add_f32 v[20:21], v[20:21], v[52:53] neg_lo:[0,1] neg_hi:[0,1]
	v_pk_add_f32 v[22:23], v[22:23], v[54:55] neg_lo:[0,1] neg_hi:[0,1]
	s_add_u32 s42, s42, 0x1000
	s_addc_u32 s43, s43, 0
	s_add_u32 s32, s32, 1
	s_sub_u32 s2, s2, 1
	s_add_u32 s61, s61, 1
	s_cmp_lg_u32 s2, 0
	s_cbranch_scc1 .Lp5_pool_block
.Lp5_pool_next_item:
	s_add_u32 s0, s0, s44
	s_branch .Lp5_pool_outer
.Lp5_pool_exit:
	v_readlane_b32 s0, v254, 15
	v_readlane_b32 s46, v255, 2
	s_nop 3
	s_lshl_b32 s0, s0, 9
	s_or_b32 s0, s0, s46
	s_add_u32 s56, s34, 0x1e900000
	s_addc_u32 s57, s35, 0
	s_add_u32 s54, s54, 0x1000
	s_addc_u32 s55, s55, 0
	v_readlane_b32 s62, v255, 33
	v_readlane_b32 s63, v255, 34
	v_readlane_b32 s64, v255, 35
	v_readlane_b32 s65, v255, 36
.Lp5_conv_outer:
	s_cmp_ge_u32 s0, 0x1a000
	s_cbranch_scc1 .Lp5_conv_exit
	s_cmp_ge_u32 s0, 0x18000
	s_cbranch_scc1 .Lp5_conv_sample
	s_lshr_b32 s58, s0, 9
	s_and_b32 s60, s0, 0x1ff
	s_cmp_ge_u32 s58, 48
	s_cselect_b32 s59, 1, 0
	s_cmp_ge_u32 s58, 96
	s_cselect_b32 s46, 1, 0
	s_add_u32 s59, s59, s46
	s_cmp_ge_u32 s58, 144
	s_cselect_b32 s46, 1, 0
	s_add_u32 s59, s59, s46
	s_mul_i32 s46, s59, 48
	s_sub_u32 s58, s58, s46
	s_mul_i32 s1, s58, 43
	s_movk_i32 s2, 43
	s_mul_i32 s3, s59, 0x810
	s_mov_b32 s9, 0
	s_mov_b64 s[52:53], 0
	s_branch .Lp5_conv_item
.Lp5_conv_sample:
	s_sub_u32 s46, s0, 0x18000
	s_and_b32 s60, s46, 0x1ff
	s_lshr_b32 s58, s46, 9
	s_lshr_b32 s59, s58, 1
	s_and_b32 s1, s58, 1
	s_lshl_b32 s1, s1, 4
	s_movk_i32 s2, 16
	s_lshl_b32 s3, s59, 5
	s_add_u32 s3, s3, 0x2040
	s_mov_b32 s9, 1
	v_readlane_b32 s52, v255, 13
	v_readlane_b32 s53, v255, 14
	s_mul_i32 s46, s59, 0xc000
	s_nop 1
	s_add_u32 s52, s52, s46
	s_addc_u32 s53, s53, 0
.Lp5_conv_item:
	v_add_u32_e32 v1, s60, v0
	v_lshlrev_b32_e32 v2, 5, v1
	v_lshlrev_b32_e32 v1, 4, v1
	s_mov_b64 s[20:21], s[62:63]
	global_load_dwordx4 v[128:131], v2, s[20:21]
	global_load_dwordx4 v[132:135], v2, s[20:21] offset:16
	s_add_u32 s20, s20, 0x4000
	s_addc_u32 s21, s21, 0
	global_load_dwordx4 v[136:139], v2, s[20:21]
	global_load_dwordx4 v[140:143], v2, s[20:21] offset:16
	s_add_u32 s20, s20, 0x4000
	s_addc_u32 s21, s21, 0
	global_load_dwordx4 v[144:147], v2, s[20:21]
	global_load_dwordx4 v[148:151], v2, s[20:21] offset:16
	s_add_u32 s20, s20, 0x4000
	s_addc_u32 s21, s21, 0
	global_load_dwordx4 v[152:155], v2, s[20:21]
	global_load_dwordx4 v[156:159], v2, s[20:21] offset:16
	s_add_u32 s20, s20, 0x4000
	s_addc_u32 s21, s21, 0
	global_load_dwordx4 v[160:163], v2, s[64:65]
	global_load_dwordx4 v[164:167], v2, s[64:65] offset:16
	s_add_i32 s29, s1, -3
	s_cmp_lt_i32 s29, 0
	s_cbranch_scc1 .Lp5_conv_hneg_0
	s_add_u32 s46, s3, s29
	s_mul_i32 s46, s46, 0x5000
	s_add_u32 s22, s54, s46
	s_addc_u32 s23, s55, 0
	global_load_dwordx4 v[180:183], v1, s[22:23]
	s_branch .Lp5_conv_hnext_0
.Lp5_conv_hneg_0:
	s_cmp_eq_u32 s9, 0
	s_cbranch_scc1 .Lp5_conv_hzero_0
	s_add_i32 s46, s29, 3
	s_lshl_b32 s46, s46, 14
	s_add_u32 s30, s52, s46
	s_addc_u32 s31, s53, 0
	global_load_dwordx4 v[176:179], v2, s[30:31]
	global_load_dwordx4 v[180:183], v2, s[30:31] offset:16
	s_branch .Lp5_conv_hnext_0

.Lp5_conv_hnext_0:
	s_add_i32 s29, s1, -2
	s_cmp_lt_i32 s29, 0
	s_cbranch_scc1 .Lp5_conv_hneg_1
	s_add_u32 s46, s3, s29
	s_mul_i32 s46, s46, 0x5000
	s_add_u32 s22, s54, s46
	s_addc_u32 s23, s55, 0
	global_load_dwordx4 v[188:191], v1, s[22:23]
	s_branch .Lp5_conv_hnext_1
.Lp5_conv_hneg_1:
	s_cmp_eq_u32 s9, 0
	s_cbranch_scc1 .Lp5_conv_hzero_1
	s_add_i32 s46, s29, 3
	s_lshl_b32 s46, s46, 14
	s_add_u32 s30, s52, s46
	s_addc_u32 s31, s53, 0
	global_load_dwordx4 v[184:187], v2, s[30:31]
	global_load_dwordx4 v[188:191], v2, s[30:31] offset:16
	s_branch .Lp5_conv_hnext_1

.Lp5_conv_hnext_1:
	s_add_i32 s29, s1, -1
	s_cmp_lt_i32 s29, 0
	s_cbranch_scc1 .Lp5_conv_hneg_2
	s_add_u32 s46, s3, s29
	s_mul_i32 s46, s46, 0x5000
	s_add_u32 s22, s54, s46
	s_addc_u32 s23, s55, 0
	global_load_dwordx4 v[196:199], v1, s[22:23]
	s_branch .Lp5_conv_hnext_2
.Lp5_conv_hneg_2:
	s_cmp_eq_u32 s9, 0
	s_cbranch_scc1 .Lp5_conv_hzero_2
	s_add_i32 s46, s29, 3
	s_lshl_b32 s46, s46, 14
	s_add_u32 s30, s52, s46
	s_addc_u32 s31, s53, 0
	global_load_dwordx4 v[192:195], v2, s[30:31]
	global_load_dwordx4 v[196:199], v2, s[30:31] offset:16
	s_branch .Lp5_conv_hnext_2

.Lp5_conv_hnext_2:
	s_mov_b32 s32, s1
	s_mov_b32 s61, 0
	s_add_u32 s46, s3, s1
	s_lshl_b32 s46, s46, 13
	s_add_u32 s42, s56, s46
	s_addc_u32 s43, s57, 0

.Lp5_conv_Edone:
	s_waitcnt vmcnt(0)
	s_cmp_lg_u32 s61, 0
	s_cbranch_scc1 .Lp5_conv_rows
	s_add_i32 s29, s1, -3
	s_cmp_lt_i32 s29, 0
	s_cbranch_scc1 .Lp5_conv_hu_0
	v_lshlrev_b32_e32 v176, 16, v180
	v_and_b32_e32 v177, 0xffff0000, v180
	v_lshlrev_b32_e32 v178, 16, v181
	v_and_b32_e32 v179, 0xffff0000, v181
	v_lshlrev_b32_e32 v180, 16, v182
	v_and_b32_e32 v181, 0xffff0000, v182
	v_lshlrev_b32_e32 v182, 16, v183
	v_and_b32_e32 v183, 0xffff0000, v183
.Lp5_conv_hu_0:
	s_add_i32 s29, s1, -2
	s_cmp_lt_i32 s29, 0
	s_cbranch_scc1 .Lp5_conv_hu_1
	v_lshlrev_b32_e32 v184, 16, v188
	v_and_b32_e32 v185, 0xffff0000, v188
	v_lshlrev_b32_e32 v186, 16, v189
	v_and_b32_e32 v187, 0xffff0000, v189
	v_lshlrev_b32_e32 v188, 16, v190
	v_and_b32_e32 v189, 0xffff0000, v190
	v_lshlrev_b32_e32 v190, 16, v191
	v_and_b32_e32 v191, 0xffff0000, v191
.Lp5_conv_hu_1:
	s_add_i32 s29, s1, -1
	s_cmp_lt_i32 s29, 0
	s_cbranch_scc1 .Lp5_conv_hu_2
	v_lshlrev_b32_e32 v192, 16, v196
	v_and_b32_e32 v193, 0xffff0000, v196
	v_lshlrev_b32_e32 v194, 16, v197
	v_and_b32_e32 v195, 0xffff0000, v197
	v_lshlrev_b32_e32 v196, 16, v198
	v_and_b32_e32 v197, 0xffff0000, v198
	v_lshlrev_b32_e32 v198, 16, v199
	v_and_b32_e32 v199, 0xffff0000, v199
.Lp5_conv_hu_2:
.Lp5_conv_rows:
	s_cmp_eq_u32 s2, 0
	s_cbranch_scc1 .Lp5_conv_next_item
	v_lshlrev_b32_e32 v168, 16, v64
	v_and_b32_e32 v169, 0xffff0000, v64
	v_lshlrev_b32_e32 v170, 16, v65
	v_and_b32_e32 v171, 0xffff0000, v65
	v_lshlrev_b32_e32 v172, 16, v66
	v_and_b32_e32 v173, 0xffff0000, v66
	v_lshlrev_b32_e32 v174, 16, v67
	v_and_b32_e32 v175, 0xffff0000, v67
	v_fma_f32 v200, v128, v176, v160
	v_fma_f32 v201, v129, v177, v161
	v_fma_f32 v202, v130, v178, v162
	v_fma_f32 v203, v131, v179, v163
	v_fma_f32 v204, v132, v180, v164
	v_fma_f32 v205, v133, v181, v165
	v_fma_f32 v206, v134, v182, v166
	v_fma_f32 v207, v135, v183, v167
	v_fmac_f32_e32 v200, v136, v184
	v_fmac_f32_e32 v201, v137, v185
	v_fmac_f32_e32 v202, v138, v186
	v_fmac_f32_e32 v203, v139, v187
	v_fmac_f32_e32 v204, v140, v188
	v_fmac_f32_e32 v205, v141, v189
	v_fmac_f32_e32 v206, v142, v190
	v_fmac_f32_e32 v207, v143, v191
	v_fmac_f32_e32 v200, v144, v192
	v_fmac_f32_e32 v201, v145, v193
	v_fmac_f32_e32 v202, v146, v194
	v_fmac_f32_e32 v203, v147, v195
	v_fmac_f32_e32 v204, v148, v196
	v_fmac_f32_e32 v205, v149, v197
	v_fmac_f32_e32 v206, v150, v198
	v_fmac_f32_e32 v207, v151, v199
	v_fmac_f32_e32 v200, v152, v168
	v_fmac_f32_e32 v201, v153, v169
	v_fmac_f32_e32 v202, v154, v170
	v_fmac_f32_e32 v203, v155, v171
	v_fmac_f32_e32 v204, v156, v172
	v_fmac_f32_e32 v205, v157, v173
	v_fmac_f32_e32 v206, v158, v174
	v_fmac_f32_e32 v207, v159, v175
	v_cvt_pk_bf16_f32 v40, v200, v201
	v_cvt_pk_bf16_f32 v41, v202, v203
	v_cvt_pk_bf16_f32 v42, v204, v205
	v_cvt_pk_bf16_f32 v43, v206, v207
	global_store_dwordx4 v1, v[40:43], s[42:43]
	s_add_u32 s42, s42, 0x2000
	s_addc_u32 s43, s43, 0
	s_add_u32 s32, s32, 1
	s_sub_u32 s2, s2, 1
	s_cmp_eq_u32 s2, 0
	s_cbranch_scc1 .Lp5_conv_next_item
	v_lshlrev_b32_e32 v176, 16, v68
	v_and_b32_e32 v177, 0xffff0000, v68
	v_lshlrev_b32_e32 v178, 16, v69
	v_and_b32_e32 v179, 0xffff0000, v69
	v_lshlrev_b32_e32 v180, 16, v70
	v_and_b32_e32 v181, 0xffff0000, v70
	v_lshlrev_b32_e32 v182, 16, v71
	v_and_b32_e32 v183, 0xffff0000, v71
	v_fma_f32 v200, v128, v184, v160
	v_fma_f32 v201, v129, v185, v161
	v_fma_f32 v202, v130, v186, v162
	v_fma_f32 v203, v131, v187, v163
	v_fma_f32 v204, v132, v188, v164
	v_fma_f32 v205, v133, v189, v165
	v_fma_f32 v206, v134, v190, v166
	v_fma_f32 v207, v135, v191, v167
	v_fmac_f32_e32 v200, v136, v192
	v_fmac_f32_e32 v201, v137, v193
	v_fmac_f32_e32 v202, v138, v194
	v_fmac_f32_e32 v203, v139, v195
	v_fmac_f32_e32 v204, v140, v196
	v_fmac_f32_e32 v205, v141, v197
	v_fmac_f32_e32 v206, v142, v198
	v_fmac_f32_e32 v207, v143, v199
	v_fmac_f32_e32 v200, v144, v168
	v_fmac_f32_e32 v201, v145, v169
	v_fmac_f32_e32 v202, v146, v170
	v_fmac_f32_e32 v203, v147, v171
	v_fmac_f32_e32 v204, v148, v172
	v_fmac_f32_e32 v205, v149, v173
	v_fmac_f32_e32 v206, v150, v174
	v_fmac_f32_e32 v207, v151, v175
	v_fmac_f32_e32 v200, v152, v176
	v_fmac_f32_e32 v201, v153, v177
	v_fmac_f32_e32 v202, v154, v178
	v_fmac_f32_e32 v203, v155, v179
	v_fmac_f32_e32 v204, v156, v180
	v_fmac_f32_e32 v205, v157, v181
	v_fmac_f32_e32 v206, v158, v182
	v_fmac_f32_e32 v207, v159, v183
	v_cvt_pk_bf16_f32 v44, v200, v201
	v_cvt_pk_bf16_f32 v45, v202, v203
	v_cvt_pk_bf16_f32 v46, v204, v205
	v_cvt_pk_bf16_f32 v47, v206, v207
	global_store_dwordx4 v1, v[44:47], s[42:43]
	s_add_u32 s42, s42, 0x2000
	s_addc_u32 s43, s43, 0
	s_add_u32 s32, s32, 1
	s_sub_u32 s2, s2, 1
	s_cmp_eq_u32 s2, 0
	s_cbranch_scc1 .Lp5_conv_next_item
	v_lshlrev_b32_e32 v184, 16, v72
	v_and_b32_e32 v185, 0xffff0000, v72
	v_lshlrev_b32_e32 v186, 16, v73
	v_and_b32_e32 v187, 0xffff0000, v73
	v_lshlrev_b32_e32 v188, 16, v74
	v_and_b32_e32 v189, 0xffff0000, v74
	v_lshlrev_b32_e32 v190, 16, v75
	v_and_b32_e32 v191, 0xffff0000, v75
	v_fma_f32 v200, v128, v192, v160
	v_fma_f32 v201, v129, v193, v161
	v_fma_f32 v202, v130, v194, v162
	v_fma_f32 v203, v131, v195, v163
	v_fma_f32 v204, v132, v196, v164
	v_fma_f32 v205, v133, v197, v165
	v_fma_f32 v206, v134, v198, v166
	v_fma_f32 v207, v135, v199, v167
	v_fmac_f32_e32 v200, v136, v168
	v_fmac_f32_e32 v201, v137, v169
	v_fmac_f32_e32 v202, v138, v170
	v_fmac_f32_e32 v203, v139, v171
	v_fmac_f32_e32 v204, v140, v172
	v_fmac_f32_e32 v205, v141, v173
	v_fmac_f32_e32 v206, v142, v174
	v_fmac_f32_e32 v207, v143, v175
	v_fmac_f32_e32 v200, v144, v176
	v_fmac_f32_e32 v201, v145, v177
	v_fmac_f32_e32 v202, v146, v178
	v_fmac_f32_e32 v203, v147, v179
	v_fmac_f32_e32 v204, v148, v180
	v_fmac_f32_e32 v205, v149, v181
	v_fmac_f32_e32 v206, v150, v182
	v_fmac_f32_e32 v207, v151, v183
	v_fmac_f32_e32 v200, v152, v184
	v_fmac_f32_e32 v201, v153, v185
	v_fmac_f32_e32 v202, v154, v186
	v_fmac_f32_e32 v203, v155, v187
	v_fmac_f32_e32 v204, v156, v188
	v_fmac_f32_e32 v205, v157, v189
	v_fmac_f32_e32 v206, v158, v190
	v_fmac_f32_e32 v207, v159, v191
	v_cvt_pk_bf16_f32 v40, v200, v201
	v_cvt_pk_bf16_f32 v41, v202, v203
	v_cvt_pk_bf16_f32 v42, v204, v205
	v_cvt_pk_bf16_f32 v43, v206, v207
	global_store_dwordx4 v1, v[40:43], s[42:43]
	s_add_u32 s42, s42, 0x2000
	s_addc_u32 s43, s43, 0
	s_add_u32 s32, s32, 1
	s_sub_u32 s2, s2, 1
	s_cmp_eq_u32 s2, 0
	s_cbranch_scc1 .Lp5_conv_next_item
	v_lshlrev_b32_e32 v192, 16, v76
	v_and_b32_e32 v193, 0xffff0000, v76
	v_lshlrev_b32_e32 v194, 16, v77
	v_and_b32_e32 v195, 0xffff0000, v77
	v_lshlrev_b32_e32 v196, 16, v78
	v_and_b32_e32 v197, 0xffff0000, v78
	v_lshlrev_b32_e32 v198, 16, v79
	v_and_b32_e32 v199, 0xffff0000, v79
	v_fma_f32 v200, v128, v168, v160
	v_fma_f32 v201, v129, v169, v161
	v_fma_f32 v202, v130, v170, v162
	v_fma_f32 v203, v131, v171, v163
	v_fma_f32 v204, v132, v172, v164
	v_fma_f32 v205, v133, v173, v165
	v_fma_f32 v206, v134, v174, v166
	v_fma_f32 v207, v135, v175, v167
	v_fmac_f32_e32 v200, v136, v176
	v_fmac_f32_e32 v201, v137, v177
	v_fmac_f32_e32 v202, v138, v178
	v_fmac_f32_e32 v203, v139, v179
	v_fmac_f32_e32 v204, v140, v180
	v_fmac_f32_e32 v205, v141, v181
	v_fmac_f32_e32 v206, v142, v182
	v_fmac_f32_e32 v207, v143, v183
	v_fmac_f32_e32 v200, v144, v184
	v_fmac_f32_e32 v201, v145, v185
	v_fmac_f32_e32 v202, v146, v186
	v_fmac_f32_e32 v203, v147, v187
	v_fmac_f32_e32 v204, v148, v188
	v_fmac_f32_e32 v205, v149, v189
	v_fmac_f32_e32 v206, v150, v190
	v_fmac_f32_e32 v207, v151, v191
	v_fmac_f32_e32 v200, v152, v192
	v_fmac_f32_e32 v201, v153, v193
	v_fmac_f32_e32 v202, v154, v194
	v_fmac_f32_e32 v203, v155, v195
	v_fmac_f32_e32 v204, v156, v196
	v_fmac_f32_e32 v205, v157, v197
	v_fmac_f32_e32 v206, v158, v198
	v_fmac_f32_e32 v207, v159, v199
	v_cvt_pk_bf16_f32 v44, v200, v201
	v_cvt_pk_bf16_f32 v45, v202, v203
	v_cvt_pk_bf16_f32 v46, v204, v205
	v_cvt_pk_bf16_f32 v47, v206, v207
	global_store_dwordx4 v1, v[44:47], s[42:43]
	s_add_u32 s42, s42, 0x2000
	s_addc_u32 s43, s43, 0
	s_add_u32 s32, s32, 1
	s_sub_u32 s2, s2, 1
	s_cmp_eq_u32 s2, 0
	s_cbranch_scc1 .Lp5_conv_next_item
	v_lshlrev_b32_e32 v168, 16, v80
	v_and_b32_e32 v169, 0xffff0000, v80
	v_lshlrev_b32_e32 v170, 16, v81
	v_and_b32_e32 v171, 0xffff0000, v81
	v_lshlrev_b32_e32 v172, 16, v82
	v_and_b32_e32 v173, 0xffff0000, v82
	v_lshlrev_b32_e32 v174, 16, v83
	v_and_b32_e32 v175, 0xffff0000, v83
	v_fma_f32 v200, v128, v176, v160
	v_fma_f32 v201, v129, v177, v161
	v_fma_f32 v202, v130, v178, v162
	v_fma_f32 v203, v131, v179, v163
	v_fma_f32 v204, v132, v180, v164
	v_fma_f32 v205, v133, v181, v165
	v_fma_f32 v206, v134, v182, v166
	v_fma_f32 v207, v135, v183, v167
	v_fmac_f32_e32 v200, v136, v184
	v_fmac_f32_e32 v201, v137, v185
	v_fmac_f32_e32 v202, v138, v186
	v_fmac_f32_e32 v203, v139, v187
	v_fmac_f32_e32 v204, v140, v188
	v_fmac_f32_e32 v205, v141, v189
	v_fmac_f32_e32 v206, v142, v190
	v_fmac_f32_e32 v207, v143, v191
	v_fmac_f32_e32 v200, v144, v192
	v_fmac_f32_e32 v201, v145, v193
	v_fmac_f32_e32 v202, v146, v194
	v_fmac_f32_e32 v203, v147, v195
	v_fmac_f32_e32 v204, v148, v196
	v_fmac_f32_e32 v205, v149, v197
	v_fmac_f32_e32 v206, v150, v198
	v_fmac_f32_e32 v207, v151, v199
	v_fmac_f32_e32 v200, v152, v168
	v_fmac_f32_e32 v201, v153, v169
	v_fmac_f32_e32 v202, v154, v170
	v_fmac_f32_e32 v203, v155, v171
	v_fmac_f32_e32 v204, v156, v172
	v_fmac_f32_e32 v205, v157, v173
	v_fmac_f32_e32 v206, v158, v174
	v_fmac_f32_e32 v207, v159, v175
	v_cvt_pk_bf16_f32 v40, v200, v201
	v_cvt_pk_bf16_f32 v41, v202, v203
	v_cvt_pk_bf16_f32 v42, v204, v205
	v_cvt_pk_bf16_f32 v43, v206, v207
	global_store_dwordx4 v1, v[40:43], s[42:43]
	s_add_u32 s42, s42, 0x2000
	s_addc_u32 s43, s43, 0
	s_add_u32 s32, s32, 1
	s_sub_u32 s2, s2, 1
	s_cmp_eq_u32 s2, 0
	s_cbranch_scc1 .Lp5_conv_next_item
	v_lshlrev_b32_e32 v176, 16, v84
	v_and_b32_e32 v177, 0xffff0000, v84
	v_lshlrev_b32_e32 v178, 16, v85
	v_and_b32_e32 v179, 0xffff0000, v85
	v_lshlrev_b32_e32 v180, 16, v86
	v_and_b32_e32 v181, 0xffff0000, v86
	v_lshlrev_b32_e32 v182, 16, v87
	v_and_b32_e32 v183, 0xffff0000, v87
	v_fma_f32 v200, v128, v184, v160
	v_fma_f32 v201, v129, v185, v161
	v_fma_f32 v202, v130, v186, v162
	v_fma_f32 v203, v131, v187, v163
	v_fma_f32 v204, v132, v188, v164
	v_fma_f32 v205, v133, v189, v165
	v_fma_f32 v206, v134, v190, v166
	v_fma_f32 v207, v135, v191, v167
	v_fmac_f32_e32 v200, v136, v192
	v_fmac_f32_e32 v201, v137, v193
	v_fmac_f32_e32 v202, v138, v194
	v_fmac_f32_e32 v203, v139, v195
	v_fmac_f32_e32 v204, v140, v196
	v_fmac_f32_e32 v205, v141, v197
	v_fmac_f32_e32 v206, v142, v198
	v_fmac_f32_e32 v207, v143, v199
	v_fmac_f32_e32 v200, v144, v168
	v_fmac_f32_e32 v201, v145, v169
	v_fmac_f32_e32 v202, v146, v170
	v_fmac_f32_e32 v203, v147, v171
	v_fmac_f32_e32 v204, v148, v172
	v_fmac_f32_e32 v205, v149, v173
	v_fmac_f32_e32 v206, v150, v174
	v_fmac_f32_e32 v207, v151, v175
	v_fmac_f32_e32 v200, v152, v176
	v_fmac_f32_e32 v201, v153, v177
	v_fmac_f32_e32 v202, v154, v178
	v_fmac_f32_e32 v203, v155, v179
	v_fmac_f32_e32 v204, v156, v180
	v_fmac_f32_e32 v205, v157, v181
	v_fmac_f32_e32 v206, v158, v182
	v_fmac_f32_e32 v207, v159, v183
	v_cvt_pk_bf16_f32 v44, v200, v201
	v_cvt_pk_bf16_f32 v45, v202, v203
	v_cvt_pk_bf16_f32 v46, v204, v205
	v_cvt_pk_bf16_f32 v47, v206, v207
	global_store_dwordx4 v1, v[44:47], s[42:43]
	s_add_u32 s42, s42, 0x2000
	s_addc_u32 s43, s43, 0
	s_add_u32 s32, s32, 1
	s_sub_u32 s2, s2, 1
	s_cmp_eq_u32 s2, 0
	s_cbranch_scc1 .Lp5_conv_next_item
	v_lshlrev_b32_e32 v184, 16, v88
	v_and_b32_e32 v185, 0xffff0000, v88
	v_lshlrev_b32_e32 v186, 16, v89
	v_and_b32_e32 v187, 0xffff0000, v89
	v_lshlrev_b32_e32 v188, 16, v90
	v_and_b32_e32 v189, 0xffff0000, v90
	v_lshlrev_b32_e32 v190, 16, v91
	v_and_b32_e32 v191, 0xffff0000, v91
	v_fma_f32 v200, v128, v192, v160
	v_fma_f32 v201, v129, v193, v161
	v_fma_f32 v202, v130, v194, v162
	v_fma_f32 v203, v131, v195, v163
	v_fma_f32 v204, v132, v196, v164
	v_fma_f32 v205, v133, v197, v165
	v_fma_f32 v206, v134, v198, v166
	v_fma_f32 v207, v135, v199, v167
	v_fmac_f32_e32 v200, v136, v168
	v_fmac_f32_e32 v201, v137, v169
	v_fmac_f32_e32 v202, v138, v170
	v_fmac_f32_e32 v203, v139, v171
	v_fmac_f32_e32 v204, v140, v172
	v_fmac_f32_e32 v205, v141, v173
	v_fmac_f32_e32 v206, v142, v174
	v_fmac_f32_e32 v207, v143, v175
	v_fmac_f32_e32 v200, v144, v176
	v_fmac_f32_e32 v201, v145, v177
	v_fmac_f32_e32 v202, v146, v178
	v_fmac_f32_e32 v203, v147, v179
	v_fmac_f32_e32 v204, v148, v180
	v_fmac_f32_e32 v205, v149, v181
	v_fmac_f32_e32 v206, v150, v182
	v_fmac_f32_e32 v207, v151, v183
	v_fmac_f32_e32 v200, v152, v184
	v_fmac_f32_e32 v201, v153, v185
	v_fmac_f32_e32 v202, v154, v186
	v_fmac_f32_e32 v203, v155, v187
	v_fmac_f32_e32 v204, v156, v188
	v_fmac_f32_e32 v205, v157, v189
	v_fmac_f32_e32 v206, v158, v190
	v_fmac_f32_e32 v207, v159, v191
	v_cvt_pk_bf16_f32 v40, v200, v201
	v_cvt_pk_bf16_f32 v41, v202, v203
	v_cvt_pk_bf16_f32 v42, v204, v205
	v_cvt_pk_bf16_f32 v43, v206, v207
	global_store_dwordx4 v1, v[40:43], s[42:43]
	s_add_u32 s42, s42, 0x2000
	s_addc_u32 s43, s43, 0
	s_add_u32 s32, s32, 1
	s_sub_u32 s2, s2, 1
	s_cmp_eq_u32 s2, 0
	s_cbranch_scc1 .Lp5_conv_next_item
	v_lshlrev_b32_e32 v192, 16, v92
	v_and_b32_e32 v193, 0xffff0000, v92
	v_lshlrev_b32_e32 v194, 16, v93
	v_and_b32_e32 v195, 0xffff0000, v93
	v_lshlrev_b32_e32 v196, 16, v94
	v_and_b32_e32 v197, 0xffff0000, v94
	v_lshlrev_b32_e32 v198, 16, v95
	v_and_b32_e32 v199, 0xffff0000, v95
	v_fma_f32 v200, v128, v168, v160
	v_fma_f32 v201, v129, v169, v161
	v_fma_f32 v202, v130, v170, v162
	v_fma_f32 v203, v131, v171, v163
	v_fma_f32 v204, v132, v172, v164
	v_fma_f32 v205, v133, v173, v165
	v_fma_f32 v206, v134, v174, v166
	v_fma_f32 v207, v135, v175, v167
	v_fmac_f32_e32 v200, v136, v176
	v_fmac_f32_e32 v201, v137, v177
	v_fmac_f32_e32 v202, v138, v178
	v_fmac_f32_e32 v203, v139, v179
	v_fmac_f32_e32 v204, v140, v180
	v_fmac_f32_e32 v205, v141, v181
	v_fmac_f32_e32 v206, v142, v182
	v_fmac_f32_e32 v207, v143, v183
	v_fmac_f32_e32 v200, v144, v184
	v_fmac_f32_e32 v201, v145, v185
	v_fmac_f32_e32 v202, v146, v186
	v_fmac_f32_e32 v203, v147, v187
	v_fmac_f32_e32 v204, v148, v188
	v_fmac_f32_e32 v205, v149, v189
	v_fmac_f32_e32 v206, v150, v190
	v_fmac_f32_e32 v207, v151, v191
	v_fmac_f32_e32 v200, v152, v192
	v_fmac_f32_e32 v201, v153, v193
	v_fmac_f32_e32 v202, v154, v194
	v_fmac_f32_e32 v203, v155, v195
	v_fmac_f32_e32 v204, v156, v196
	v_fmac_f32_e32 v205, v157, v197
	v_fmac_f32_e32 v206, v158, v198
	v_fmac_f32_e32 v207, v159, v199
	v_cvt_pk_bf16_f32 v44, v200, v201
	v_cvt_pk_bf16_f32 v45, v202, v203
	v_cvt_pk_bf16_f32 v46, v204, v205
	v_cvt_pk_bf16_f32 v47, v206, v207
	global_store_dwordx4 v1, v[44:47], s[42:43]
	s_add_u32 s42, s42, 0x2000
	s_addc_u32 s43, s43, 0
	s_add_u32 s32, s32, 1
	s_sub_u32 s2, s2, 1
	s_cmp_eq_u32 s2, 0
	s_cbranch_scc1 .Lp5_conv_next_item
	v_lshlrev_b32_e32 v168, 16, v96
	v_and_b32_e32 v169, 0xffff0000, v96
	v_lshlrev_b32_e32 v170, 16, v97
	v_and_b32_e32 v171, 0xffff0000, v97
	v_lshlrev_b32_e32 v172, 16, v98
	v_and_b32_e32 v173, 0xffff0000, v98
	v_lshlrev_b32_e32 v174, 16, v99
	v_and_b32_e32 v175, 0xffff0000, v99
	v_fma_f32 v200, v128, v176, v160
	v_fma_f32 v201, v129, v177, v161
	v_fma_f32 v202, v130, v178, v162
	v_fma_f32 v203, v131, v179, v163
	v_fma_f32 v204, v132, v180, v164
	v_fma_f32 v205, v133, v181, v165
	v_fma_f32 v206, v134, v182, v166
	v_fma_f32 v207, v135, v183, v167
	v_fmac_f32_e32 v200, v136, v184
	v_fmac_f32_e32 v201, v137, v185
	v_fmac_f32_e32 v202, v138, v186
	v_fmac_f32_e32 v203, v139, v187
	v_fmac_f32_e32 v204, v140, v188
	v_fmac_f32_e32 v205, v141, v189
	v_fmac_f32_e32 v206, v142, v190
	v_fmac_f32_e32 v207, v143, v191
	v_fmac_f32_e32 v200, v144, v192
	v_fmac_f32_e32 v201, v145, v193
	v_fmac_f32_e32 v202, v146, v194
	v_fmac_f32_e32 v203, v147, v195
	v_fmac_f32_e32 v204, v148, v196
	v_fmac_f32_e32 v205, v149, v197
	v_fmac_f32_e32 v206, v150, v198
	v_fmac_f32_e32 v207, v151, v199
	v_fmac_f32_e32 v200, v152, v168
	v_fmac_f32_e32 v201, v153, v169
	v_fmac_f32_e32 v202, v154, v170
	v_fmac_f32_e32 v203, v155, v171
	v_fmac_f32_e32 v204, v156, v172
	v_fmac_f32_e32 v205, v157, v173
	v_fmac_f32_e32 v206, v158, v174
	v_fmac_f32_e32 v207, v159, v175
	v_cvt_pk_bf16_f32 v40, v200, v201
	v_cvt_pk_bf16_f32 v41, v202, v203
	v_cvt_pk_bf16_f32 v42, v204, v205
	v_cvt_pk_bf16_f32 v43, v206, v207
	global_store_dwordx4 v1, v[40:43], s[42:43]
	s_add_u32 s42, s42, 0x2000
	s_addc_u32 s43, s43, 0
	s_add_u32 s32, s32, 1
	s_sub_u32 s2, s2, 1
	s_cmp_eq_u32 s2, 0
	s_cbranch_scc1 .Lp5_conv_next_item
	v_lshlrev_b32_e32 v176, 16, v100
	v_and_b32_e32 v177, 0xffff0000, v100
	v_lshlrev_b32_e32 v178, 16, v101
	v_and_b32_e32 v179, 0xffff0000, v101
	v_lshlrev_b32_e32 v180, 16, v102
	v_and_b32_e32 v181, 0xffff0000, v102
	v_lshlrev_b32_e32 v182, 16, v103
	v_and_b32_e32 v183, 0xffff0000, v103
	v_fma_f32 v200, v128, v184, v160
	v_fma_f32 v201, v129, v185, v161
	v_fma_f32 v202, v130, v186, v162
	v_fma_f32 v203, v131, v187, v163
	v_fma_f32 v204, v132, v188, v164
	v_fma_f32 v205, v133, v189, v165
	v_fma_f32 v206, v134, v190, v166
	v_fma_f32 v207, v135, v191, v167
	v_fmac_f32_e32 v200, v136, v192
	v_fmac_f32_e32 v201, v137, v193
	v_fmac_f32_e32 v202, v138, v194
	v_fmac_f32_e32 v203, v139, v195
	v_fmac_f32_e32 v204, v140, v196
	v_fmac_f32_e32 v205, v141, v197
	v_fmac_f32_e32 v206, v142, v198
	v_fmac_f32_e32 v207, v143, v199
	v_fmac_f32_e32 v200, v144, v168
	v_fmac_f32_e32 v201, v145, v169
	v_fmac_f32_e32 v202, v146, v170
	v_fmac_f32_e32 v203, v147, v171
	v_fmac_f32_e32 v204, v148, v172
	v_fmac_f32_e32 v205, v149, v173
	v_fmac_f32_e32 v206, v150, v174
	v_fmac_f32_e32 v207, v151, v175
	v_fmac_f32_e32 v200, v152, v176
	v_fmac_f32_e32 v201, v153, v177
	v_fmac_f32_e32 v202, v154, v178
	v_fmac_f32_e32 v203, v155, v179
	v_fmac_f32_e32 v204, v156, v180
	v_fmac_f32_e32 v205, v157, v181
	v_fmac_f32_e32 v206, v158, v182
	v_fmac_f32_e32 v207, v159, v183
	v_cvt_pk_bf16_f32 v44, v200, v201
	v_cvt_pk_bf16_f32 v45, v202, v203
	v_cvt_pk_bf16_f32 v46, v204, v205
	v_cvt_pk_bf16_f32 v47, v206, v207
	global_store_dwordx4 v1, v[44:47], s[42:43]
	s_add_u32 s42, s42, 0x2000
	s_addc_u32 s43, s43, 0
	s_add_u32 s32, s32, 1
	s_sub_u32 s2, s2, 1
	s_cmp_eq_u32 s2, 0
	s_cbranch_scc1 .Lp5_conv_next_item
	v_lshlrev_b32_e32 v184, 16, v104
	v_and_b32_e32 v185, 0xffff0000, v104
	v_lshlrev_b32_e32 v186, 16, v105
	v_and_b32_e32 v187, 0xffff0000, v105
	v_lshlrev_b32_e32 v188, 16, v106
	v_and_b32_e32 v189, 0xffff0000, v106
	v_lshlrev_b32_e32 v190, 16, v107
	v_and_b32_e32 v191, 0xffff0000, v107
	v_fma_f32 v200, v128, v192, v160
	v_fma_f32 v201, v129, v193, v161
	v_fma_f32 v202, v130, v194, v162
	v_fma_f32 v203, v131, v195, v163
	v_fma_f32 v204, v132, v196, v164
	v_fma_f32 v205, v133, v197, v165
	v_fma_f32 v206, v134, v198, v166
	v_fma_f32 v207, v135, v199, v167
	v_fmac_f32_e32 v200, v136, v168
	v_fmac_f32_e32 v201, v137, v169
	v_fmac_f32_e32 v202, v138, v170
	v_fmac_f32_e32 v203, v139, v171
	v_fmac_f32_e32 v204, v140, v172
	v_fmac_f32_e32 v205, v141, v173
	v_fmac_f32_e32 v206, v142, v174
	v_fmac_f32_e32 v207, v143, v175
	v_fmac_f32_e32 v200, v144, v176
	v_fmac_f32_e32 v201, v145, v177
	v_fmac_f32_e32 v202, v146, v178
	v_fmac_f32_e32 v203, v147, v179
	v_fmac_f32_e32 v204, v148, v180
	v_fmac_f32_e32 v205, v149, v181
	v_fmac_f32_e32 v206, v150, v182
	v_fmac_f32_e32 v207, v151, v183
	v_fmac_f32_e32 v200, v152, v184
	v_fmac_f32_e32 v201, v153, v185
	v_fmac_f32_e32 v202, v154, v186
	v_fmac_f32_e32 v203, v155, v187
	v_fmac_f32_e32 v204, v156, v188
	v_fmac_f32_e32 v205, v157, v189
	v_fmac_f32_e32 v206, v158, v190
	v_fmac_f32_e32 v207, v159, v191
	v_cvt_pk_bf16_f32 v40, v200, v201
	v_cvt_pk_bf16_f32 v41, v202, v203
	v_cvt_pk_bf16_f32 v42, v204, v205
	v_cvt_pk_bf16_f32 v43, v206, v207
	global_store_dwordx4 v1, v[40:43], s[42:43]
	s_add_u32 s42, s42, 0x2000
	s_addc_u32 s43, s43, 0
	s_add_u32 s32, s32, 1
	s_sub_u32 s2, s2, 1
	s_cmp_eq_u32 s2, 0
	s_cbranch_scc1 .Lp5_conv_next_item
	v_lshlrev_b32_e32 v192, 16, v108
	v_and_b32_e32 v193, 0xffff0000, v108
	v_lshlrev_b32_e32 v194, 16, v109
	v_and_b32_e32 v195, 0xffff0000, v109
	v_lshlrev_b32_e32 v196, 16, v110
	v_and_b32_e32 v197, 0xffff0000, v110
	v_lshlrev_b32_e32 v198, 16, v111
	v_and_b32_e32 v199, 0xffff0000, v111
	v_fma_f32 v200, v128, v168, v160
	v_fma_f32 v201, v129, v169, v161
	v_fma_f32 v202, v130, v170, v162
	v_fma_f32 v203, v131, v171, v163
	v_fma_f32 v204, v132, v172, v164
	v_fma_f32 v205, v133, v173, v165
	v_fma_f32 v206, v134, v174, v166
	v_fma_f32 v207, v135, v175, v167
	v_fmac_f32_e32 v200, v136, v176
	v_fmac_f32_e32 v201, v137, v177
	v_fmac_f32_e32 v202, v138, v178
	v_fmac_f32_e32 v203, v139, v179
	v_fmac_f32_e32 v204, v140, v180
	v_fmac_f32_e32 v205, v141, v181
	v_fmac_f32_e32 v206, v142, v182
	v_fmac_f32_e32 v207, v143, v183
	v_fmac_f32_e32 v200, v144, v184
	v_fmac_f32_e32 v201, v145, v185
	v_fmac_f32_e32 v202, v146, v186
	v_fmac_f32_e32 v203, v147, v187
	v_fmac_f32_e32 v204, v148, v188
	v_fmac_f32_e32 v205, v149, v189
	v_fmac_f32_e32 v206, v150, v190
	v_fmac_f32_e32 v207, v151, v191
	v_fmac_f32_e32 v200, v152, v192
	v_fmac_f32_e32 v201, v153, v193
	v_fmac_f32_e32 v202, v154, v194
	v_fmac_f32_e32 v203, v155, v195
	v_fmac_f32_e32 v204, v156, v196
	v_fmac_f32_e32 v205, v157, v197
	v_fmac_f32_e32 v206, v158, v198
	v_fmac_f32_e32 v207, v159, v199
	v_cvt_pk_bf16_f32 v44, v200, v201
	v_cvt_pk_bf16_f32 v45, v202, v203
	v_cvt_pk_bf16_f32 v46, v204, v205
	v_cvt_pk_bf16_f32 v47, v206, v207
	global_store_dwordx4 v1, v[44:47], s[42:43]
	s_add_u32 s42, s42, 0x2000
	s_addc_u32 s43, s43, 0
	s_add_u32 s32, s32, 1
	s_sub_u32 s2, s2, 1
	s_cmp_eq_u32 s2, 0
	s_cbranch_scc1 .Lp5_conv_next_item
	v_lshlrev_b32_e32 v168, 16, v112
	v_and_b32_e32 v169, 0xffff0000, v112
	v_lshlrev_b32_e32 v170, 16, v113
	v_and_b32_e32 v171, 0xffff0000, v113
	v_lshlrev_b32_e32 v172, 16, v114
	v_and_b32_e32 v173, 0xffff0000, v114
	v_lshlrev_b32_e32 v174, 16, v115
	v_and_b32_e32 v175, 0xffff0000, v115
	v_fma_f32 v200, v128, v176, v160
	v_fma_f32 v201, v129, v177, v161
	v_fma_f32 v202, v130, v178, v162
	v_fma_f32 v203, v131, v179, v163
	v_fma_f32 v204, v132, v180, v164
	v_fma_f32 v205, v133, v181, v165
	v_fma_f32 v206, v134, v182, v166
	v_fma_f32 v207, v135, v183, v167
	v_fmac_f32_e32 v200, v136, v184
	v_fmac_f32_e32 v201, v137, v185
	v_fmac_f32_e32 v202, v138, v186
	v_fmac_f32_e32 v203, v139, v187
	v_fmac_f32_e32 v204, v140, v188
	v_fmac_f32_e32 v205, v141, v189
	v_fmac_f32_e32 v206, v142, v190
	v_fmac_f32_e32 v207, v143, v191
	v_fmac_f32_e32 v200, v144, v192
	v_fmac_f32_e32 v201, v145, v193
	v_fmac_f32_e32 v202, v146, v194
	v_fmac_f32_e32 v203, v147, v195
	v_fmac_f32_e32 v204, v148, v196
	v_fmac_f32_e32 v205, v149, v197
	v_fmac_f32_e32 v206, v150, v198
	v_fmac_f32_e32 v207, v151, v199
	v_fmac_f32_e32 v200, v152, v168
	v_fmac_f32_e32 v201, v153, v169
	v_fmac_f32_e32 v202, v154, v170
	v_fmac_f32_e32 v203, v155, v171
	v_fmac_f32_e32 v204, v156, v172
	v_fmac_f32_e32 v205, v157, v173
	v_fmac_f32_e32 v206, v158, v174
	v_fmac_f32_e32 v207, v159, v175
	v_cvt_pk_bf16_f32 v40, v200, v201
	v_cvt_pk_bf16_f32 v41, v202, v203
	v_cvt_pk_bf16_f32 v42, v204, v205
	v_cvt_pk_bf16_f32 v43, v206, v207
	global_store_dwordx4 v1, v[40:43], s[42:43]
	s_add_u32 s42, s42, 0x2000
	s_addc_u32 s43, s43, 0
	s_add_u32 s32, s32, 1
	s_sub_u32 s2, s2, 1
	s_cmp_eq_u32 s2, 0
	s_cbranch_scc1 .Lp5_conv_next_item
	v_lshlrev_b32_e32 v176, 16, v116
	v_and_b32_e32 v177, 0xffff0000, v116
	v_lshlrev_b32_e32 v178, 16, v117
	v_and_b32_e32 v179, 0xffff0000, v117
	v_lshlrev_b32_e32 v180, 16, v118
	v_and_b32_e32 v181, 0xffff0000, v118
	v_lshlrev_b32_e32 v182, 16, v119
	v_and_b32_e32 v183, 0xffff0000, v119
	v_fma_f32 v200, v128, v184, v160
	v_fma_f32 v201, v129, v185, v161
	v_fma_f32 v202, v130, v186, v162
	v_fma_f32 v203, v131, v187, v163
	v_fma_f32 v204, v132, v188, v164
	v_fma_f32 v205, v133, v189, v165
	v_fma_f32 v206, v134, v190, v166
	v_fma_f32 v207, v135, v191, v167
	v_fmac_f32_e32 v200, v136, v192
	v_fmac_f32_e32 v201, v137, v193
	v_fmac_f32_e32 v202, v138, v194
	v_fmac_f32_e32 v203, v139, v195
	v_fmac_f32_e32 v204, v140, v196
	v_fmac_f32_e32 v205, v141, v197
	v_fmac_f32_e32 v206, v142, v198
	v_fmac_f32_e32 v207, v143, v199
	v_fmac_f32_e32 v200, v144, v168
	v_fmac_f32_e32 v201, v145, v169
	v_fmac_f32_e32 v202, v146, v170
	v_fmac_f32_e32 v203, v147, v171
	v_fmac_f32_e32 v204, v148, v172
	v_fmac_f32_e32 v205, v149, v173
	v_fmac_f32_e32 v206, v150, v174
	v_fmac_f32_e32 v207, v151, v175
	v_fmac_f32_e32 v200, v152, v176
	v_fmac_f32_e32 v201, v153, v177
	v_fmac_f32_e32 v202, v154, v178
	v_fmac_f32_e32 v203, v155, v179
	v_fmac_f32_e32 v204, v156, v180
	v_fmac_f32_e32 v205, v157, v181
	v_fmac_f32_e32 v206, v158, v182
	v_fmac_f32_e32 v207, v159, v183
	v_cvt_pk_bf16_f32 v44, v200, v201
	v_cvt_pk_bf16_f32 v45, v202, v203
	v_cvt_pk_bf16_f32 v46, v204, v205
	v_cvt_pk_bf16_f32 v47, v206, v207
	global_store_dwordx4 v1, v[44:47], s[42:43]
	s_add_u32 s42, s42, 0x2000
	s_addc_u32 s43, s43, 0
	s_add_u32 s32, s32, 1
	s_sub_u32 s2, s2, 1
	s_cmp_eq_u32 s2, 0
	s_cbranch_scc1 .Lp5_conv_next_item
	v_lshlrev_b32_e32 v184, 16, v120
	v_and_b32_e32 v185, 0xffff0000, v120
	v_lshlrev_b32_e32 v186, 16, v121
	v_and_b32_e32 v187, 0xffff0000, v121
	v_lshlrev_b32_e32 v188, 16, v122
	v_and_b32_e32 v189, 0xffff0000, v122
	v_lshlrev_b32_e32 v190, 16, v123
	v_and_b32_e32 v191, 0xffff0000, v123
	v_fma_f32 v200, v128, v192, v160
	v_fma_f32 v201, v129, v193, v161
	v_fma_f32 v202, v130, v194, v162
	v_fma_f32 v203, v131, v195, v163
	v_fma_f32 v204, v132, v196, v164
	v_fma_f32 v205, v133, v197, v165
	v_fma_f32 v206, v134, v198, v166
	v_fma_f32 v207, v135, v199, v167
	v_fmac_f32_e32 v200, v136, v168
	v_fmac_f32_e32 v201, v137, v169
	v_fmac_f32_e32 v202, v138, v170
	v_fmac_f32_e32 v203, v139, v171
	v_fmac_f32_e32 v204, v140, v172
	v_fmac_f32_e32 v205, v141, v173
	v_fmac_f32_e32 v206, v142, v174
	v_fmac_f32_e32 v207, v143, v175
	v_fmac_f32_e32 v200, v144, v176
	v_fmac_f32_e32 v201, v145, v177
	v_fmac_f32_e32 v202, v146, v178
	v_fmac_f32_e32 v203, v147, v179
	v_fmac_f32_e32 v204, v148, v180
	v_fmac_f32_e32 v205, v149, v181
	v_fmac_f32_e32 v206, v150, v182
	v_fmac_f32_e32 v207, v151, v183
	v_fmac_f32_e32 v200, v152, v184
	v_fmac_f32_e32 v201, v153, v185
	v_fmac_f32_e32 v202, v154, v186
	v_fmac_f32_e32 v203, v155, v187
	v_fmac_f32_e32 v204, v156, v188
	v_fmac_f32_e32 v205, v157, v189
	v_fmac_f32_e32 v206, v158, v190
	v_fmac_f32_e32 v207, v159, v191
	v_cvt_pk_bf16_f32 v40, v200, v201
	v_cvt_pk_bf16_f32 v41, v202, v203
	v_cvt_pk_bf16_f32 v42, v204, v205
	v_cvt_pk_bf16_f32 v43, v206, v207
	global_store_dwordx4 v1, v[40:43], s[42:43]
	s_add_u32 s42, s42, 0x2000
	s_addc_u32 s43, s43, 0
	s_add_u32 s32, s32, 1
	s_sub_u32 s2, s2, 1
	s_cmp_eq_u32 s2, 0
	s_cbranch_scc1 .Lp5_conv_next_item
	v_lshlrev_b32_e32 v192, 16, v124
	v_and_b32_e32 v193, 0xffff0000, v124
	v_lshlrev_b32_e32 v194, 16, v125
	v_and_b32_e32 v195, 0xffff0000, v125
	v_lshlrev_b32_e32 v196, 16, v126
	v_and_b32_e32 v197, 0xffff0000, v126
	v_lshlrev_b32_e32 v198, 16, v127
	v_and_b32_e32 v199, 0xffff0000, v127
	v_fma_f32 v200, v128, v168, v160
	v_fma_f32 v201, v129, v169, v161
	v_fma_f32 v202, v130, v170, v162
	v_fma_f32 v203, v131, v171, v163
	v_fma_f32 v204, v132, v172, v164
	v_fma_f32 v205, v133, v173, v165
	v_fma_f32 v206, v134, v174, v166
	v_fma_f32 v207, v135, v175, v167
	v_fmac_f32_e32 v200, v136, v176
	v_fmac_f32_e32 v201, v137, v177
	v_fmac_f32_e32 v202, v138, v178
	v_fmac_f32_e32 v203, v139, v179
	v_fmac_f32_e32 v204, v140, v180
	v_fmac_f32_e32 v205, v141, v181
	v_fmac_f32_e32 v206, v142, v182
	v_fmac_f32_e32 v207, v143, v183
	v_fmac_f32_e32 v200, v144, v184
	v_fmac_f32_e32 v201, v145, v185
	v_fmac_f32_e32 v202, v146, v186
	v_fmac_f32_e32 v203, v147, v187
	v_fmac_f32_e32 v204, v148, v188
	v_fmac_f32_e32 v205, v149, v189
	v_fmac_f32_e32 v206, v150, v190
	v_fmac_f32_e32 v207, v151, v191
	v_fmac_f32_e32 v200, v152, v192
	v_fmac_f32_e32 v201, v153, v193
	v_fmac_f32_e32 v202, v154, v194
	v_fmac_f32_e32 v203, v155, v195
	v_fmac_f32_e32 v204, v156, v196
	v_fmac_f32_e32 v205, v157, v197
	v_fmac_f32_e32 v206, v158, v198
	v_fmac_f32_e32 v207, v159, v199
	v_cvt_pk_bf16_f32 v44, v200, v201
	v_cvt_pk_bf16_f32 v45, v202, v203
	v_cvt_pk_bf16_f32 v46, v204, v205
	v_cvt_pk_bf16_f32 v47, v206, v207
	global_store_dwordx4 v1, v[44:47], s[42:43]
	s_add_u32 s42, s42, 0x2000
	s_addc_u32 s43, s43, 0
	s_add_u32 s32, s32, 1
	s_sub_u32 s2, s2, 1
	s_add_u32 s61, s61, 1
	s_cmp_lg_u32 s2, 0
	s_cbranch_scc1 .Lp5_conv_block

.Lp5_conv_exit:
	v_readlane_b32 s45, v254, 15
	v_readlane_b32 s46, v255, 2
	s_nop 3
	s_lshl_b32 s45, s45, 9
	s_or_b32 s45, s45, s46
	v_mbcnt_lo_u32_b32 v0, -1, 0
	v_mbcnt_hi_u32_b32 v0, -1, v0
	v_add_u32_e32 v62, s45, v0
	s_mov_b64 s[4:5], exec
